# m3qkv: M3 Q/K/V all loaded coalesced; V row-major swizzled in LDS, read via ds_read_b64_tr_b16; MFMA sections prefetch LDS operands with counted waits
# baseline (speedup 1.0000x reference)
;   __host__ __device__ __forceinline__ float* G() const { return (float*)(wsl() + OFF_G); }
;   __host__ __device__ __forceinline__ bf16_t* Wgu(int i) const { return (bf16_t*)(wsl() + OFF_FFN + (size_t)i * FFN_STRIDE); }
;   __host__ __device__ __forceinline__ bf16_t* Wd(int i) const { return (bf16_t*)(wsl() + OFF_FFN + (size_t)i * FFN_STRIDE + WGU_B); }
;   __host__ __device__ __forceinline__ bf16_t* Wein() const { return (bf16_t*)(wsl() + OFF_WEIN); }
;   __host__ __device__ __forceinline__ bf16_t* H() const { return (bf16_t*)(wsl() + OFF_H); }
;   __host__ __device__ __forceinline__ bf16_t* ACT() const { return (bf16_t*)(wsl() + OFF_ACT); }
; __device__ __forceinline__ void m3_phase(const Params& p, char* smem) {
;   const int tid = otid(), lane = tid & 63, w = tid >> 6, fr = lane & 15, fq = lane >> 4;
;   bf16_t* Qs = (bf16_t*)smem;
;   bf16_t* Ks = Qs + 64 * 136;
;   bf16_t* Vt = Ks + 64 * 136;
;   bf16_t* Cs = Vt + 128 * 72;
;   bf16_t* Sw = Cs + 128 * 136;
;   float* hs = (float*)(Sw + 64 * 72);
;   float* cs = hs + 64 * 132;
;   float* rt = cs + 64;
;   float* wint = rt + 64;
;   float* emt = wint + 64;
;   float* qn = emt + 64;
;   float* denp = qn + 64;
;   float* ns = denp + 128;
;   bf16_t* MIX = p.H();
; __device__ __forceinline__ void run_phase(const Params& p, int ph, char* smem) {
;     ...
;   switch (kind) {
;     case K_P0: if (!KEN(K_P0)) break; p0_phase(p, smem); break;
;     case K_NORMMOD: if (!KEN(K_NORMMOD)) break; normmod_phase(p, a0, a1, a2); break;
;     case K_FFN_UP: if (!KEN(K_FFN_UP)) break;
;       fe.outb = p.ACT(); fe.ldo = DFF;
;       fast_gemm<EPI_SWIGLU>(p, fe, p.H(), D, p.Wgu(a0), D, 22, a1, smem); break;
;     case K_FFN_DOWN: if (!KEN(K_FFN_DOWN)) break;
;       fe.layer = a0 >> 1; fe.slot = (a0 & 1) ? 8 : 2; fe.scale = 0.5f; fe.xin = a2 ? p.x : nullptr;
;       fast_gemm<EPI_RESID>(p, fe, p.ACT(), DFF, p.Wd(a0), DFF, 4, 1, smem);
;       if (a1) ctx_gemm<EPI_RESID>(p, fe, p.ACT(), DFF, p.Wd(a0), DFF, 0, 16, smem);
;       break;
;     case K_E1: if (!KEN(K_E1)) break; fe.outb = p.ACT(); fe.outf = p.G();
;       fast_gemm<EPI_E1>(p, fe, p.H(), D, p.Wein(), D, 11, 0, smem); break;
;     case K_M1: if (!KEN(K_M1)) break; m1_phase(p, smem); break;
;     case K_M2: if (!KEN(K_M2)) break; m2_phase(p); break;
;     case K_M3: if (!KEN(K_M3)) break; m3_phase(p, smem); break;
.LBB0_478:
	s_andn2_b64 vcc, exec, s[2:3]
	s_cbranch_vccnz .LBB0_1070
	s_and_b32 s2, 0xffff, s18
	v_writelane_b32 v255, s2, 58
	s_cmp_lt_i32 s2, 4
	s_mov_b64 s[2:3], -1
	s_cbranch_scc1 .LBB0_820
	v_readlane_b32 s2, v255, 58
	s_cmp_lt_i32 s2, 6
	s_mov_b64 s[2:3], -1
	s_cbranch_scc1 .LBB0_756
	v_readlane_b32 s2, v255, 58
	s_cmp_gt_i32 s2, 6
	s_mov_b64 s[2:3], -1
	s_cbranch_scc0 .LBB0_550
	v_mov_b32_e32 v32, v164
	s_mov_b32 s4, s82
	s_cmpk_gt_i32 s4, 0x41f
	s_cbranch_scc1 .LBB0_549
	v_and_b32_e32 v13, 64, v231
	v_xor_b32_e32 v12, 1, v231
	v_add_u32_e32 v14, 64, v13
	v_cmp_lt_i32_e32 vcc, v12, v14
	s_waitcnt lgkmcnt(0)
	v_ashrrev_i32_e32 v1, 6, v32
	v_and_b32_e32 v5, 3, v1
	v_cndmask_b32_e32 v12, v231, v12, vcc
	v_lshlrev_b32_e32 v53, 2, v12
	v_xor_b32_e32 v12, 2, v231
	v_cmp_lt_i32_e32 vcc, v12, v14
	v_lshlrev_b32_e32 v7, 4, v5
	v_lshlrev_b32_e32 v5, 6, v5
	v_cndmask_b32_e32 v12, v231, v12, vcc
	v_lshlrev_b32_e32 v54, 2, v12
	v_xor_b32_e32 v12, 4, v231
	v_cmp_lt_i32_e32 vcc, v12, v14
	v_readlane_b32 s8, v255, 31
	s_movk_i32 s7, 0x110
	v_cndmask_b32_e32 v12, v231, v12, vcc
	v_lshlrev_b32_e32 v55, 2, v12
	v_xor_b32_e32 v12, 8, v231
	v_cmp_lt_i32_e32 vcc, v12, v14
	v_and_b32_e32 v15, 7, v32
	v_lshlrev_b32_e32 v17, 5, v15
	v_cndmask_b32_e32 v12, v231, v12, vcc
	v_lshlrev_b32_e32 v56, 2, v12
	v_and_b32_e32 v12, 0xffffff00, v32
	v_add3_u32 v5, s8, v12, v5
	v_ashrrev_i32_e32 v12, 3, v32
	v_mul_lo_u32 v16, v12, s7
	v_add3_u32 v57, 0, v16, v17
	v_xor_b32_e32 v17, 32, v231
	v_cmp_lt_i32_e32 vcc, v17, v14
	v_lshlrev_b32_e32 v4, 4, v32
	v_and_b32_e32 v166, 0xf0, v4
	v_cndmask_b32_e32 v17, v231, v17, vcc
	v_lshlrev_b32_e32 v67, 2, v17
	v_xor_b32_e32 v17, 16, v231
	v_cmp_lt_i32_e32 vcc, v17, v14
	s_load_dwordx2 s[88:89], s[0:1], 0xf0
	s_load_dwordx2 s[86:87], s[0:1], 0x98
	v_cndmask_b32_e32 v14, v231, v17, vcc
	v_lshlrev_b32_e32 v68, 2, v14
	v_add_u32_e32 v14, -1, v231
	v_cmp_lt_i32_e32 vcc, v14, v13
	v_add_u32_e32 v4, 0, v166
	s_mov_b32 s15, 0xd000
	v_cndmask_b32_e32 v14, v14, v231, vcc
	v_lshlrev_b32_e32 v70, 2, v14
	v_add_u32_e32 v14, -2, v231
	v_cmp_lt_i32_e32 vcc, v14, v13
	v_and_b32_e32 v34, 63, v32
	v_and_b32_e32 v0, 15, v32
	v_cndmask_b32_e32 v14, v14, v231, vcc
	v_lshlrev_b32_e32 v71, 2, v14
	v_add_u32_e32 v14, -4, v231
	v_cmp_lt_i32_e32 vcc, v14, v13
	v_and_b32_e32 v9, 48, v32
	v_lshrrev_b32_e32 v10, 2, v32
	v_cndmask_b32_e32 v14, v14, v231, vcc
	v_lshlrev_b32_e32 v72, 2, v14
	v_add_u32_e32 v14, -8, v231
	v_cmp_lt_i32_e32 vcc, v14, v13
	v_readlane_b32 s3, v255, 32
	v_mul_u32_u24_e32 v2, 0x88, v34
	v_cndmask_b32_e32 v14, v14, v231, vcc
	v_lshlrev_b32_e32 v73, 2, v14
	v_add_u32_e32 v14, -16, v231
	v_cmp_lt_i32_e32 vcc, v14, v13
	v_or_b32_e32 v8, v7, v0
	v_add_u32_e32 v35, 0, v9
	v_cndmask_b32_e32 v14, v14, v231, vcc
	v_lshlrev_b32_e32 v74, 2, v14
	v_subrev_u32_e32 v14, 32, v231
	v_cmp_lt_i32_e32 vcc, v14, v13
	v_and_b32_e32 v10, 12, v10
	v_lshl_add_u32 v58, v15, 6, s3
	v_cndmask_b32_e32 v13, v14, v231, vcc
	v_add_u32_e32 v14, 0x200, v32
	v_ashrrev_i32_e32 v17, 3, v14
	v_ashrrev_i32_e32 v14, 4, v14
	v_lshlrev_b32_e32 v42, 7, v14
	v_mul_lo_u32 v14, v14, s7
	v_add3_u32 v79, v4, v14, s15
	v_add_u32_e32 v14, 0x400, v32
	v_ashrrev_i32_e32 v14, 4, v14
	v_lshlrev_b32_e32 v44, 7, v14
	v_mul_lo_u32 v14, v14, s7
	v_lshl_add_u32 v64, v32, 2, s3
	s_movk_i32 s3, 0x1080
	v_ashrrev_i32_e32 v18, 4, v32
	v_add3_u32 v80, v4, v14, s15
	v_add_u32_e32 v14, 0x600, v32
	s_waitcnt lgkmcnt(0)
	s_add_u32 s5, s88, 0x5190000
	v_lshl_add_u32 v2, v2, 1, 0
	s_movk_i32 s2, 0xfef2
	v_ashrrev_i32_e32 v6, 8, v32
	v_mad_u32_u24 v52, v8, s7, v35
	v_or_b32_e32 v11, v7, v10
	v_mul_u32_u24_e32 v8, 0x90, v8
	v_readlane_b32 s9, v255, 33
	v_lshlrev_b32_e32 v66, 3, v1
	v_mul_lo_u32 v1, v1, s3
	s_movk_i32 s3, 0x90
	v_lshlrev_b32_e32 v40, 7, v18
	v_mul_lo_u32 v18, v18, s7
	v_ashrrev_i32_e32 v14, 4, v14
	v_mov_b32_e32 v22, 0x120
	s_addc_u32 s6, s89, 0
	v_mad_i32_i24 v3, v34, s2, v2
	v_cmp_eq_u32_e64 s[44:45], 0, v0
	v_add3_u32 v59, s9, v8, v9
	v_lshl_or_b32 v8, v6, 6, v0
	s_add_i32 s2, 0, 0x20000
	v_add3_u32 v78, v4, v18, s15
	v_lshlrev_b32_e32 v46, 7, v14
	v_mul_lo_u32 v14, v14, s7
	v_lshl_or_b32 v0, v6, 5, v0
	v_or_b32_e32 v18, 1, v11
	v_or_b32_e32 v20, 2, v11
	v_mad_u32_u24 v89, v11, s3, v22
	v_or_b32_e32 v22, 3, v11
	v_readlane_b32 s10, v255, 34
	v_readlane_b32 s11, v255, 35
	v_readlane_b32 s12, v255, 36
	v_readlane_b32 s13, v255, 37
	v_add3_u32 v81, v4, v14, s15
	v_mul_lo_u32 v4, v0, s7
	v_or_b32_e32 v6, 16, v0
	v_lshl_add_u32 v82, v0, 2, s2
	v_lshl_add_u32 v83, v0, 1, s9
	v_cmp_le_i32_e64 s[60:61], v0, v11
	v_cmp_le_i32_e64 s[62:63], v0, v18
	v_cmp_le_i32_e64 s[64:65], v0, v20
	v_cmp_le_i32_e64 s[66:67], v0, v22
	v_lshlrev_b32_e32 v0, 2, v22
	v_add_u32_e32 v90, s10, v0
	v_mov_b32_e32 v23, 0x1b0
	s_waitcnt vmcnt(0)
;   __host__ __device__ __forceinline__ bf16_t* ACT() const { return (bf16_t*)(wsl() + OFF_ACT); }
; #define MFMA16(a, b, c) __builtin_amdgcn_mfma_f32_16x16x32_bf16(a, b, c, 0, 0, 0)
; __device__ __forceinline__ void m3_phase(const Params& p, char* smem) {
;     ...
; #pragma unroll
;       for (int i = 0; i < 2; ++i) {
;         int idx = tid + i * NTHR;
;         int r = idx & 63, fc = (idx >> 6) * 8;
;         int row = rowbase + mchunk_tok(dir, j, r);
;         const bf16_t* src = p.ACT() + (size_t)row * PW;
;         uint4 qv = *(const uint4*)(src + 672 + h * 128 + fc);
;         uint4 kv = *(const uint4*)(src + 1184 + h * 128 + fc);
;         uint4 vv = *(const uint4*)(src + 1696 + h * 128 + fc);
;         *(uint4*)(Qs + r * 136 + fc) = qv;
;         *(uint4*)(Ks + r * 136 + fc) = kv;
;         const bf16_t* ve = (const bf16_t*)&vv;
; #pragma unroll
;         for (int e = 0; e < 8; ++e) Vt[(fc + e) * 72 + r] = ve[e];
;     ...
;       {
;         const int mi = w & 3, nh = w >> 2;
;         f32x4 a1[4], a2[4];
; #pragma unroll
;         for (int q = 0; q < 4; ++q) { a1[q] = (f32x4){0.f, 0.f, 0.f, 0.f}; a2[q] = (f32x4){0.f, 0.f, 0.f, 0.f}; }
; #pragma unroll
;         for (int ks = 0; ks < 2; ++ks) {
;           bf16x8 a = *(const bf16x8*)(Sw + (mi * 16 + fr) * 72 + ks * 32 + fq * 8);
; #pragma unroll
;           for (int q = 0; q < 4; ++q) {
;             bf16x8 bb = *(const bf16x8*)(Vt + ((nh * 4 + q) * 16 + fr) * 72 + ks * 32 + fq * 8);
;             a1[q] = MFMA16(a, bb, a1[q]);
;           }
;         }
	v_add_u32_e32 v113, s11, v0
	v_add_u32_e32 v114, s12, v0
	v_add_u32_e32 v115, s13, v0
	v_add_u32_e32 v116, s8, v0
	v_bitop3_b32 v0, v7, 60, v10 bitop3:0x36
	v_cmp_eq_u32_e64 s[46:47], 0, v15
	v_lshlrev_b32_e32 v15, 2, v34
	v_readlane_b32 s14, v255, 38
	v_mad_u32_u24 v91, v11, s3, v23
	v_lshl_add_u32 v92, v6, 2, s2
	v_cmp_le_i32_e64 s[68:69], v6, v11
	v_lshlrev_b32_e32 v23, 1, v6
	v_cmp_le_i32_e64 s[70:71], v6, v18
	v_cmp_le_i32_e64 s[72:73], v6, v20
	v_cmp_le_i32_e64 s[74:75], v6, v22
	v_mul_lo_u32 v6, v8, s3
	v_mul_lo_u32 v97, v8, s7
	v_lshlrev_b32_e32 v8, 2, v8
	v_mul_u32_u24_e32 v0, 0x210, v0
	v_add_u32_e32 v60, s2, v15
	v_add3_u32 v121, s14, v0, v8
	v_or_b32_e32 v0, 1, v66
	s_movk_i32 s2, 0x210
	v_add_u32_e32 v16, s14, v15
	v_mul_lo_u32 v0, v0, s2
	v_add_u32_e32 v69, v16, v1
	v_add3_u32 v122, s14, v1, v15
	v_add_u32_e32 v1, 0x210, v0
	v_add_u32_e32 v125, v16, v1
	v_add3_u32 v126, s14, v1, v15
	v_add_u32_e32 v1, 0x420, v0
	v_add_u32_e32 v127, v16, v1
	v_add3_u32 v128, s14, v1, v15
	v_add_u32_e32 v1, 0x630, v0
	s_add_u32 s90, s88, 0x7290000
	v_add_u32_e32 v129, v16, v1
	v_add3_u32 v130, s14, v1, v15
	v_add_u32_e32 v1, 0x840, v0
	s_addc_u32 s91, s89, 0
	v_lshl_add_u32 v65, v12, 2, s13
	v_and_b32_e32 v36, -8, v12
	v_or_b32_e32 v12, 7, v12
	v_and_b32_e32 v38, -8, v17
	v_or_b32_e32 v17, 7, v17
	v_lshlrev_b32_e32 v14, 2, v11
	v_mul_u32_u24_e32 v85, 0x90, v11
	v_lshlrev_b32_e32 v19, 2, v18
	v_mad_u32_u24 v87, v11, s3, s3
	v_mul_u32_u24_e32 v11, 0x210, v11
	v_add_u32_e32 v123, v16, v0
	v_add3_u32 v124, s14, v0, v15
	v_add_u32_e32 v131, v16, v1
	v_add3_u32 v132, s14, v1, v15
	v_add_u32_e32 v1, 0xa50, v0
	v_add_u32_e32 v0, 0xc60, v0
	s_add_u32 s92, s88, 0x11186000
	v_ashrrev_i32_e32 v33, 31, v32
	v_lshlrev_b32_e32 v75, 2, v13
	v_lshl_add_u32 v76, v36, 1, v2
	v_mul_lo_u32 v13, v36, s3
	v_mul_lo_u32 v12, v12, s3
	v_lshl_add_u32 v77, v38, 1, v2
	v_lshrrev_b32_e32 v208, 4, v32
	v_and_b32_e32 v209, 15, v32
	v_lshlrev_b32_e32 v209, 4, v209
	v_sub_u32_e32 v210, v208, v34
	v_mul_i32_i24_e32 v210, 0x1600, v210
	v_add_u32_e32 v196, v210, v209
	v_ashrrev_i32_e32 v197, 31, v196
	v_add_u32_e32 v198, 0x2c000, v196
	v_ashrrev_i32_e32 v199, 31, v198
	v_sub_u32_e32 v200, v209, v210
	v_ashrrev_i32_e32 v201, 31, v200
	v_add_u32_e32 v202, 0xfffd4000, v200
	v_ashrrev_i32_e32 v203, 31, v202
	v_mul_u32_u24_e32 v178, 0x110, v208
	v_add_u32_e32 v178, v178, v209
	v_lshrrev_b32_e32 v214, 3, v208
	v_and_b32_e32 v214, 1, v214
	v_lshlrev_b32_e32 v214, 7, v214
	v_xor_b32_e32 v214, v214, v209
	v_mul_u32_u24_e32 v171, 0x120, v208
	v_add_u32_e32 v171, v171, v214
	v_and_b32_e32 v214, 15, v231
	v_lshrrev_b32_e32 v215, 4, v231
	v_lshrrev_b32_e32 v179, 2, v214
	v_lshl_add_u32 v179, v215, 3, v179
	v_mul_u32_u24_e32 v179, 0x120, v179
	v_and_b32_e32 v214, 3, v214
	v_lshl_add_u32 v179, v214, 3, v179
	v_lshrrev_b32_e32 v214, 8, v32
	v_xor_b32_e32 v214, v214, v215
	v_and_b32_e32 v214, 1, v214
	v_lshl_add_u32 v179, v214, 7, v179
	v_mul_lo_u32 v2, v38, s3
	v_mul_lo_u32 v17, v17, s3
	v_add_u32_e32 v84, s10, v14
	v_add_u32_e32 v86, s10, v19
	v_add_u32_e32 v98, s11, v14
	v_add_u32_e32 v99, s8, v14
	v_add_u32_e32 v100, s13, v14
	v_add_u32_e32 v101, s12, v14
	v_bitop3_b32 v14, v7, 63, v10 bitop3:0x36
	v_add3_u32 v102, s14, v11, v8
	v_add_u32_e32 v103, s11, v19
	v_add_u32_e32 v104, s12, v19
	v_add_u32_e32 v105, s13, v19
	v_add_u32_e32 v106, s8, v19
	v_bitop3_b32 v11, v7, 62, v10 bitop3:0x36
	v_bitop3_b32 v19, v7, 61, v10 bitop3:0x36
	v_add_u32_e32 v133, v16, v1
	v_add3_u32 v134, s14, v1, v15
	v_add_u32_e32 v135, v16, v0
	v_add3_u32 v136, s14, v0, v15
	v_lshl_add_u64 v[0:1], s[88:89], 0, v[166:167]
	s_mov_b64 s[2:3], 0xcd50000
	s_addc_u32 s93, s89, 0
	v_lshlrev_b32_e32 v21, 2, v20
	v_add_u32_e32 v18, 0x1100, v97
	v_mul_u32_u24_e32 v14, 0x210, v14
	v_mul_u32_u24_e32 v11, 0x210, v11
	v_mul_u32_u24_e32 v19, 0x210, v19
	v_lshl_add_u64 v[48:49], v[0:1], 0, s[2:3]
	s_add_u32 s7, s88, 0x115cb200
	v_lshl_add_u64 v[0:1], v[32:33], 2, s[88:89]
	s_mov_b64 s[2:3], 0x114bf000
	v_cmp_lt_u32_e64 s[40:41], 63, v32
	v_cmp_gt_i32_e64 s[42:43], s85, v32
	v_add_u32_e32 v61, s10, v15
	v_add_u32_e32 v62, s11, v15
	v_add_u32_e32 v63, s12, v15
	v_cmp_eq_u32_e64 s[48:49], 0, v34
	v_cmp_gt_u32_e64 s[50:51], 2, v34
	v_cmp_gt_u32_e64 s[52:53], 4, v34
	v_cmp_gt_u32_e64 s[54:55], 8, v34
	v_cmp_gt_u32_e64 s[56:57], 16, v34
	v_cmp_gt_u32_e64 s[58:59], 32, v34
	v_ashrrev_i32_e32 v37, 31, v36
	v_ashrrev_i32_e32 v39, 31, v38
	v_ashrrev_i32_e32 v41, 31, v40
	v_ashrrev_i32_e32 v43, 31, v42
	v_ashrrev_i32_e32 v45, 31, v44
	v_ashrrev_i32_e32 v47, 31, v46
	v_add_u32_e32 v88, s10, v21
	v_add3_u32 v93, s9, v85, v23
	v_add3_u32 v94, s9, v87, v23
	v_add3_u32 v95, s9, v89, v23
	v_add3_u32 v96, s9, v91, v23
	v_add_u32_e32 v107, 0x210, v102
	v_add_u32_e32 v108, s11, v21
	v_add_u32_e32 v109, s12, v21
	v_add_u32_e32 v110, s13, v21
	v_add_u32_e32 v111, s8, v21
	v_add_u32_e32 v112, 0x420, v102
	v_add_u32_e32 v117, 0x630, v102
	v_add3_u32 v118, s14, v14, v8
	v_add3_u32 v119, s14, v11, v8
	v_add3_u32 v120, s14, v19, v8
	s_addc_u32 s8, s89, 0
	v_lshl_add_u64 v[50:51], v[0:1], 0, s[2:3]
	s_lshl_b32 s9, s4, 6
	s_sub_i32 s10, 0, s4
	v_lshlrev_b32_e32 v166, 1, v34
	v_add_u32_e32 v33, v3, v13
	v_add_u32_e32 v137, v3, v12
	v_add_u32_e32 v138, v3, v2
	v_add_u32_e32 v139, v3, v17
	v_add_u32_e32 v140, v35, v4
	v_add_u32_e32 v141, v5, v9
	v_add_u32_e32 v142, v35, v6
	v_add_u32_e32 v143, v35, v18
	v_mov_b32_e32 v144, v34
	v_mov_b32_e32 v145, v32
	s_branch .LBB0_485
; #define MFMA16(a, b, c) __builtin_amdgcn_mfma_f32_16x16x32_bf16(a, b, c, 0, 0, 0)
; __device__ __forceinline__ void m3_phase(const Params& p, char* smem) {
;     ...
;       {
;         const int mi = w & 3, nh = w >> 2;
;         f32x4 a1[4], a2[4];
; #pragma unroll
;         for (int q = 0; q < 4; ++q) { a1[q] = (f32x4){0.f, 0.f, 0.f, 0.f}; a2[q] = (f32x4){0.f, 0.f, 0.f, 0.f}; }
; #pragma unroll
;         for (int ks = 0; ks < 2; ++ks) {
;           bf16x8 a = *(const bf16x8*)(Sw + (mi * 16 + fr) * 72 + ks * 32 + fq * 8);
; #pragma unroll
;           for (int q = 0; q < 4; ++q) {
;             bf16x8 bb = *(const bf16x8*)(Vt + ((nh * 4 + q) * 16 + fr) * 72 + ks * 32 + fq * 8);
;             a1[q] = MFMA16(a, bb, a1[q]);
;           }
;         }
; #pragma unroll
;         for (int ks = 0; ks < 4; ++ks) {
;           bf16x8 a = *(const bf16x8*)(Qs + (mi * 16 + fr) * 136 + ks * 32 + fq * 8);
; #pragma unroll
;           for (int q = 0; q < 4; ++q) {
;             bf16x8 bb = *(const bf16x8*)(Cs + ((nh * 4 + q) * 16 + fr) * 136 + ks * 32 + fq * 8);
;             a2[q] = MFMA16(a, bb, a2[q]);
;           }
;         }
.LBB0_484:
	s_or_b64 exec, exec, s[2:3]
	s_waitcnt lgkmcnt(0)
	s_barrier
	s_mov_b64 s[14:15], 0x7291140
	s_add_u32 s94, s5, s30
	s_addc_u32 s95, s6, 0
	s_brev_b32 s16, 60
	s_mov_b32 s12, 0x800000
	s_add_i32 s4, s4, s80
	s_sub_i32 s10, s10, s80
	s_movk_i32 s84, 0x1600
	s_cmpk_gt_i32 s4, 0x41f
	ds_read_b128 v[160:163], v59
	ds_read_b64_tr_b16 v[172:173], v179 offset:34816
	ds_read_b64_tr_b16 v[174:175], v179 offset:35968
	ds_read_b64_tr_b16 v[204:205], v179 offset:34848
	ds_read_b64_tr_b16 v[206:207], v179 offset:36000
	ds_read_b64_tr_b16 v[208:209], v179 offset:34880
	ds_read_b64_tr_b16 v[210:211], v179 offset:36032
	ds_read_b64_tr_b16 v[212:213], v179 offset:34912
	ds_read_b64_tr_b16 v[214:215], v179 offset:36064
	ds_read_b128 v[236:239], v59 offset:64
	ds_read_b64_tr_b16 v[240:241], v179 offset:44032
	ds_read_b64_tr_b16 v[242:243], v179 offset:45184
	s_waitcnt lgkmcnt(5)
	v_mfma_f32_16x16x32_bf16 v[20:23], v[160:163], v[208:211], 0
	ds_read_b64_tr_b16 v[244:245], v179 offset:44064
	ds_read_b64_tr_b16 v[246:247], v179 offset:45216
	ds_read_b64_tr_b16 v[248:249], v179 offset:44096
	ds_read_b64_tr_b16 v[250:251], v179 offset:45248
	v_mfma_f32_16x16x32_bf16 v[4:7], v[160:163], v[172:175], 0
	ds_read_b64_tr_b16 v[208:209], v179 offset:44128
	ds_read_b64_tr_b16 v[210:211], v179 offset:45280
	v_mfma_f32_16x16x32_bf16 v[8:11], v[160:163], v[204:207], 0
	ds_read_b128 v[172:175], v52
	s_waitcnt lgkmcnt(10)
	v_mfma_f32_16x16x32_bf16 v[0:3], v[160:163], v[212:215], 0
	ds_read_b128 v[204:207], v150 offset:53248
	ds_read_b128 v[160:163], v150 offset:57600
	s_waitcnt lgkmcnt(9)
	v_mfma_f32_16x16x32_bf16 v[12:15], v[236:239], v[240:243], v[4:7]
	ds_read_b128 v[212:215], v143 offset:61952
	s_waitcnt lgkmcnt(8)
	v_mfma_f32_16x16x32_bf16 v[16:19], v[236:239], v[244:247], v[8:11]
	ds_read_b128 v[240:243], v150 offset:61952
	s_waitcnt lgkmcnt(7)
	v_mfma_f32_16x16x32_bf16 v[4:7], v[236:239], v[248:251], v[20:23]
	ds_read_b128 v[244:247], v52 offset:64
	s_waitcnt lgkmcnt(6)
	v_mfma_f32_16x16x32_bf16 v[0:3], v[236:239], v[208:211], v[0:3]
	ds_read_b128 v[248:251], v150 offset:53312
	ds_read_b128 v[236:239], v150 offset:57664
	s_waitcnt lgkmcnt(6)
	v_mfma_f32_16x16x32_bf16 v[20:23], v[172:175], v[204:207], 0
	ds_read_b128 v[208:211], v150 offset:62016
	s_waitcnt lgkmcnt(6)
	v_mfma_f32_16x16x32_bf16 v[24:27], v[172:175], v[160:163], 0
	ds_read_b128 v[204:207], v143 offset:62016
	s_waitcnt lgkmcnt(5)
	v_mfma_f32_16x16x32_bf16 v[28:31], v[172:175], v[240:243], 0
	ds_read_b128 v[160:163], v52 offset:128
	v_mfma_f32_16x16x32_bf16 v[8:11], v[172:175], v[212:215], 0
	ds_read_b128 v[240:243], v150 offset:53376
	ds_read_b128 v[172:175], v150 offset:57728
	s_waitcnt lgkmcnt(6)
	v_mfma_f32_16x16x32_bf16 v[20:23], v[244:247], v[248:251], v[20:23]
	ds_read_b128 v[212:215], v150 offset:62080
	s_waitcnt lgkmcnt(6)
	v_mfma_f32_16x16x32_bf16 v[24:27], v[244:247], v[236:239], v[24:27]
	ds_read_b128 v[248:251], v143 offset:62080
	s_waitcnt lgkmcnt(6)
	v_mfma_f32_16x16x32_bf16 v[28:31], v[244:247], v[208:211], v[28:31]
	ds_read_b128 v[236:239], v52 offset:192
	s_waitcnt lgkmcnt(6)
	v_mfma_f32_16x16x32_bf16 v[8:11], v[244:247], v[204:207], v[8:11]
	ds_read_b128 v[208:211], v150 offset:53440
	ds_read_b128 v[244:247], v150 offset:57792
	s_waitcnt lgkmcnt(6)
	v_mfma_f32_16x16x32_bf16 v[20:23], v[160:163], v[240:243], v[20:23]
	ds_read_b128 v[204:207], v150 offset:62144
	s_waitcnt lgkmcnt(6)
	v_mfma_f32_16x16x32_bf16 v[24:27], v[160:163], v[172:175], v[24:27]
	ds_read_b128 v[240:243], v143 offset:62144
	s_waitcnt lgkmcnt(6)
	v_mfma_f32_16x16x32_bf16 v[152:155], v[160:163], v[212:215], v[28:31]
	s_waitcnt lgkmcnt(5)
	v_mfma_f32_16x16x32_bf16 v[8:11], v[160:163], v[248:251], v[8:11]
	s_waitcnt lgkmcnt(3)
	v_mfma_f32_16x16x32_bf16 v[28:31], v[236:239], v[208:211], v[20:23]
	s_waitcnt lgkmcnt(2)
	v_mfma_f32_16x16x32_bf16 v[24:27], v[236:239], v[244:247], v[24:27]
	s_waitcnt lgkmcnt(1)
	v_mfma_f32_16x16x32_bf16 v[20:23], v[236:239], v[204:207], v[152:155]
	s_waitcnt lgkmcnt(0)
	v_mfma_f32_16x16x32_bf16 v[8:11], v[236:239], v[240:243], v[8:11]
	ds_read_b32 v148, v98
	ds_read2st64_b32 v[146:147], v99 offset1:1
	s_waitcnt lgkmcnt(1)
	v_fma_f32 v12, v28, v148, v12
	s_waitcnt lgkmcnt(0)
	v_add_f32_e32 v146, v146, v147
	ds_read_b32 v147, v100
	v_fma_f32 v16, v24, v148, v16
	v_fma_f32 v4, v20, v148, v4
	v_fma_f32 v0, v148, v8, v0
	s_waitcnt lgkmcnt(0)
	v_fmac_f32_e32 v146, v148, v147
	ds_read_b32 v147, v101
	s_waitcnt lgkmcnt(0)
	v_max_f32_e32 v147, v147, v147
	v_max_f32_e64 v146, |v146|, v147
	v_div_scale_f32 v147, s[2:3], v146, v146, 1.0
	v_rcp_f32_e32 v149, v147
	s_nop 0
	v_fma_f32 v150, -v147, v149, 1.0
	v_fmac_f32_e32 v149, v150, v149
	v_div_scale_f32 v150, vcc, 1.0, v146, 1.0
	v_mul_f32_e32 v151, v150, v149
	v_fma_f32 v152, -v147, v151, v150
	v_fmac_f32_e32 v151, v152, v149
	v_fma_f32 v147, -v147, v151, v150
	v_div_fmas_f32 v147, v147, v149, v151
	v_div_fixup_f32 v149, v147, v146, 1.0
	ds_read2_b32 v[146:147], v118 offset1:16
	s_waitcnt lgkmcnt(0)
	v_fma_f32 v12, v12, v149, v146
	v_fmac_f32_e32 v147, v16, v149
	ds_write2_b32 v118, v12, v147 offset1:16
	ds_read2_b32 v[146:147], v118 offset0:32 offset1:48
	s_waitcnt lgkmcnt(0)
	v_fma_f32 v4, v4, v149, v146
	v_fmac_f32_e32 v147, v0, v149
	ds_write2_b32 v118, v4, v147 offset0:32 offset1:48
	ds_read_b32 v0, v103
	ds_read_b32 v4, v104
	ds_read_b32 v8, v105
	ds_read2st64_b32 v[146:147], v106 offset1:1
	s_waitcnt lgkmcnt(2)
	v_max_f32_e32 v4, v4, v4
	s_waitcnt lgkmcnt(0)
;   __host__ __device__ __forceinline__ bf16_t* ACT() const { return (bf16_t*)(wsl() + OFF_ACT); }
; __device__ __forceinline__ float bf2f(bf16_t h) { return __uint_as_float(((uint32_t)h) << 16); }
; __device__ __forceinline__ float sigmoidf_(float x) { return __builtin_amdgcn_rcpf(1.0f + __expf(-x)); }
; __device__ __forceinline__ void m3_phase(const Params& p, char* smem) {
;     ...
; #pragma unroll
;         for (int jj = 0; jj < 4; ++jj) {
;           int t = mi * 16 + fq * 4 + jj;
;           float wi = wint[t];
;           float den = denp[t] + denp[64 + t] + wi * qn[t];
;           float inv = 1.0f / fmaxf(fabsf(den), emt[t]);
;           int tl = (dir == 0) ? t : (63 - t);
; #pragma unroll
;           for (int q = 0; q < 4; ++q) {
;             int v = (nh * 4 + q) * 16 + fr;
;             float hv = (a1[q][jj] + wi * a2[q][jj]) * inv;
;             if (dir == 0) hs[tl * 132 + v] = hv; else hs[tl * 132 + v] += hv;
;           }
;         }
;       }
;       __syncthreads();
;     }
;     for (int q = 0; q < 8; ++q) {
;       int tl = w * 8 + q;
;       float v0 = hs[tl * 132 + lane], v1 = hs[tl * 132 + 64 + lane];
;       float ss = wave_sum(v0 * v0 + v1 * v1);
;       float rstd = rsqrtf(ss * (1.0f / 128.0f) + 1e-6f);
;       int row = rowbase + c * 64 + tl;
;       const bf16_t* po = p.ACT() + (size_t)row * PW + 2208 + h * 128;
;       float o0 = bf2f(po[lane]), o1 = bf2f(po[64 + lane]);
;       float y0 = v0 * rstd * p.mlstm_out_g[h * 128 + lane] * sigmoidf_(o0);
	v_add_f32_e32 v12, v147, v146
	v_fmac_f32_e32 v12, v0, v8
	v_max_f32_e64 v4, |v12|, v4
	v_div_scale_f32 v8, s[2:3], v4, v4, 1.0
	v_rcp_f32_e32 v12, v8
	s_nop 0
	v_fma_f32 v16, -v8, v12, 1.0
	v_fmac_f32_e32 v12, v16, v12
	v_div_scale_f32 v16, vcc, 1.0, v4, 1.0
	v_mul_f32_e32 v20, v16, v12
	v_fma_f32 v24, -v8, v20, v16
	v_fmac_f32_e32 v20, v24, v12
	v_fma_f32 v8, -v8, v20, v16
	v_div_fmas_f32 v8, v8, v12, v20
	v_div_fixup_f32 v8, v8, v4, 1.0
	v_fma_f32 v4, v29, v0, v13
	ds_read2_b32 v[12:13], v119 offset1:16
	s_waitcnt lgkmcnt(0)
	v_fma_f32 v4, v4, v8, v12
	v_fma_f32 v12, v25, v0, v17
	v_fmac_f32_e32 v13, v12, v8
	ds_write2_b32 v119, v4, v13 offset1:16
	v_fma_f32 v12, v21, v0, v5
	ds_read2_b32 v[4:5], v119 offset0:32 offset1:48
	v_fma_f32 v0, v9, v0, v1
	s_waitcnt lgkmcnt(0)
	v_fma_f32 v4, v12, v8, v4
	v_fmac_f32_e32 v5, v0, v8
	ds_write2_b32 v119, v4, v5 offset0:32 offset1:48
	ds_read_b32 v4, v108
	ds_read_b32 v5, v109
	ds_read_b32 v8, v110
	ds_read2st64_b32 v[0:1], v111 offset1:1
	s_waitcnt lgkmcnt(3)
	v_fma_f32 v6, v22, v4, v6
	v_fma_f32 v2, v10, v4, v2
	s_waitcnt lgkmcnt(0)
	v_add_f32_e32 v0, v1, v0
	v_fmac_f32_e32 v0, v4, v8
	v_max_f32_e32 v1, v5, v5
	v_max_f32_e64 v0, |v0|, v1
	v_div_scale_f32 v1, s[2:3], v0, v0, 1.0
	v_rcp_f32_e32 v5, v1
	s_nop 0
	v_fma_f32 v8, -v1, v5, 1.0
	v_fmac_f32_e32 v5, v8, v5
	v_div_scale_f32 v8, vcc, 1.0, v0, 1.0
	v_mul_f32_e32 v9, v8, v5
	v_fma_f32 v12, -v1, v9, v8
	v_fmac_f32_e32 v9, v12, v5
	v_fma_f32 v1, -v1, v9, v8
	v_div_fmas_f32 v1, v1, v5, v9
	v_div_fixup_f32 v5, v1, v0, 1.0
	ds_read2_b32 v[0:1], v120 offset1:16
	v_fma_f32 v8, v30, v4, v14
	s_waitcnt lgkmcnt(0)
	v_fma_f32 v0, v8, v5, v0
	v_fma_f32 v8, v26, v4, v18
	v_fmac_f32_e32 v1, v8, v5
	ds_write2_b32 v120, v0, v1 offset1:16
	ds_read2_b32 v[0:1], v120 offset0:32 offset1:48
	s_waitcnt lgkmcnt(0)
	v_fma_f32 v0, v6, v5, v0
	v_fmac_f32_e32 v1, v2, v5
	ds_write2_b32 v120, v0, v1 offset0:32 offset1:48
	ds_read_b32 v2, v113
	ds_read_b32 v4, v114
	ds_read_b32 v5, v115
	ds_read2st64_b32 v[0:1], v116 offset1:1
	s_waitcnt lgkmcnt(3)
	v_fmac_f32_e32 v15, v31, v2
	v_fmac_f32_e32 v19, v27, v2
	v_fmac_f32_e32 v7, v23, v2
	s_waitcnt lgkmcnt(0)
	v_add_f32_e32 v0, v1, v0
	v_fmac_f32_e32 v0, v2, v5
	v_max_f32_e32 v1, v4, v4
	v_max_f32_e64 v0, |v0|, v1
	v_div_scale_f32 v1, s[2:3], v0, v0, 1.0
	v_rcp_f32_e32 v4, v1
	v_fmac_f32_e32 v3, v11, v2
	v_add_u32_e32 v2, s11, v66
	s_mov_b32 s11, 0x7291000
	v_fma_f32 v5, -v1, v4, 1.0
	v_fmac_f32_e32 v4, v5, v4
	v_div_scale_f32 v5, vcc, 1.0, v0, 1.0
	v_mul_f32_e32 v6, v5, v4
	v_fma_f32 v8, -v1, v6, v5
	v_fmac_f32_e32 v6, v8, v4
	v_fma_f32 v1, -v1, v6, v5
	v_div_fmas_f32 v1, v1, v4, v6
	v_div_fixup_f32 v4, v1, v0, 1.0
	ds_read2_b32 v[0:1], v121 offset1:16
	s_waitcnt lgkmcnt(0)
	v_fma_f32 v0, v15, v4, v0
	v_fmac_f32_e32 v1, v19, v4
	ds_write2_b32 v121, v0, v1 offset1:16
	ds_read2_b32 v[0:1], v121 offset0:32 offset1:48
	s_waitcnt lgkmcnt(0)
	v_fma_f32 v0, v7, v4, v0
	v_fmac_f32_e32 v1, v3, v4
	ds_write2_b32 v121, v0, v1 offset0:32 offset1:48
	v_or_b32_e32 v0, s13, v34
	v_lshlrev_b32_e32 v0, 2, v0
	s_waitcnt lgkmcnt(0)
	s_barrier
	global_load_dword v13, v0, s[86:87]
	global_load_dword v12, v0, s[86:87] offset:256
	v_mov_b64_e32 v[0:1], s[88:89]
	s_movk_i32 s13, 0x1600
	v_mad_i64_i32 v[6:7], s[2:3], v2, s13, v[0:1]
	v_lshl_add_u64 v[6:7], v[6:7], 0, s[30:31]
	v_lshl_add_u64 v[6:7], v[6:7], 0, v[166:167]
	v_lshl_add_u64 v[10:11], v[6:7], 0, s[14:15]
	v_add_co_u32_e32 v6, vcc, s11, v6
	ds_read_b32 v8, v69
	ds_read_b32 v9, v122 offset:256
	v_addc_co_u32_e32 v7, vcc, 0, v7, vcc
	v_add_co_u32_e32 v180, vcc, 0x1600, v6
	s_nop 1
	v_addc_co_u32_e32 v181, vcc, 0, v7, vcc
	global_load_ushort v182, v[180:181], off offset:320
	v_add_co_u32_e32 v180, vcc, 0x1600, v10
	s_nop 1
	v_addc_co_u32_e32 v181, vcc, 0, v11, vcc
	global_load_ushort v183, v[180:181], off offset:128
	v_add_co_u32_e32 v180, vcc, 0x2c00, v6
	s_nop 1
	v_addc_co_u32_e32 v181, vcc, 0, v7, vcc
	global_load_ushort v184, v[180:181], off offset:320
	v_add_co_u32_e32 v180, vcc, 0x2c00, v10
	s_nop 1
	v_addc_co_u32_e32 v181, vcc, 0, v11, vcc
	global_load_ushort v185, v[180:181], off offset:128
	v_add_co_u32_e32 v180, vcc, 0x4200, v6
	s_nop 1
	v_addc_co_u32_e32 v181, vcc, 0, v7, vcc
	global_load_ushort v186, v[180:181], off offset:320
	v_add_co_u32_e32 v180, vcc, 0x4200, v10
	s_nop 1
	v_addc_co_u32_e32 v181, vcc, 0, v11, vcc
	global_load_ushort v187, v[180:181], off offset:128
	v_add_co_u32_e32 v180, vcc, 0x5800, v6
	s_nop 1
	v_addc_co_u32_e32 v181, vcc, 0, v7, vcc
	global_load_ushort v188, v[180:181], off offset:320
	v_add_co_u32_e32 v180, vcc, 0x5800, v10
	s_nop 1
	v_addc_co_u32_e32 v181, vcc, 0, v11, vcc
	global_load_ushort v189, v[180:181], off offset:128
	v_add_co_u32_e32 v180, vcc, 0x6e00, v6
	s_nop 1
	v_addc_co_u32_e32 v181, vcc, 0, v7, vcc
	global_load_ushort v190, v[180:181], off offset:320
	v_add_co_u32_e32 v180, vcc, 0x6e00, v10
	s_nop 1
	v_addc_co_u32_e32 v181, vcc, 0, v11, vcc
	global_load_ushort v191, v[180:181], off offset:128
	v_add_co_u32_e32 v180, vcc, 0x8400, v6
	s_nop 1
	v_addc_co_u32_e32 v181, vcc, 0, v7, vcc
	global_load_ushort v192, v[180:181], off offset:320
	v_add_co_u32_e32 v180, vcc, 0x8400, v10
	s_nop 1
	v_addc_co_u32_e32 v181, vcc, 0, v11, vcc
	global_load_ushort v193, v[180:181], off offset:128
	v_add_co_u32_e32 v180, vcc, 0x9a00, v6
	s_nop 1
	v_addc_co_u32_e32 v181, vcc, 0, v7, vcc
	global_load_ushort v194, v[180:181], off offset:320
	v_add_co_u32_e32 v180, vcc, 0x9a00, v10
	s_nop 1
	v_addc_co_u32_e32 v181, vcc, 0, v11, vcc
	global_load_ushort v195, v[180:181], off offset:128
	global_load_ushort v6, v[6:7], off offset:320
	v_ashrrev_i32_e32 v3, 31, v2
	global_load_ushort v7, v[10:11], off offset:128
	s_waitcnt lgkmcnt(0)
;   __host__ __device__ __forceinline__ bf16_t* ACT() const { return (bf16_t*)(wsl() + OFF_ACT); }
; __device__ __forceinline__ float bf2f(bf16_t h) { return __uint_as_float(((uint32_t)h) << 16); }
; __device__ __forceinline__ float sigmoidf_(float x) { return __builtin_amdgcn_rcpf(1.0f + __expf(-x)); }
; __device__ __forceinline__ void m3_phase(const Params& p, char* smem) {
;     ...
;     for (int q = 0; q < 8; ++q) {
;       int tl = w * 8 + q;
;       float v0 = hs[tl * 132 + lane], v1 = hs[tl * 132 + 64 + lane];
;       float ss = wave_sum(v0 * v0 + v1 * v1);
;       float rstd = rsqrtf(ss * (1.0f / 128.0f) + 1e-6f);
;       int row = rowbase + c * 64 + tl;
;       const bf16_t* po = p.ACT() + (size_t)row * PW + 2208 + h * 128;
;       float o0 = bf2f(po[lane]), o1 = bf2f(po[64 + lane]);
;       float y0 = v0 * rstd * p.mlstm_out_g[h * 128 + lane] * sigmoidf_(o0);
;       float y1 = v1 * rstd * p.mlstm_out_g[h * 128 + 64 + lane] * sigmoidf_(o1);
;       MIX[(size_t)row * D + 512 + h * 128 + lane] = f2bf(y0);
;       MIX[(size_t)row * D + 512 + h * 128 + 64 + lane] = f2bf(y1);
;     }
	v_pk_mul_f32 v[4:5], v[8:9], v[8:9]
	s_mov_b32 s2, 0x358637bd
	v_mov_b32_e32 v17, v4
	s_waitcnt vmcnt(1)
	v_lshlrev_b32_e32 v6, 16, v6
	v_mul_f32_e32 v6, 0xbfb8aa3b, v6
	v_exp_f32_e32 v6, v6
	s_waitcnt vmcnt(0)
	v_lshlrev_b32_e32 v7, 16, v7
	v_add_f32_e32 v6, 1.0, v6
	v_rcp_f32_e32 v18, v6
	v_mul_f32_e32 v6, 0xbfb8aa3b, v7
	v_exp_f32_e32 v6, v6
	s_nop 0
	v_add_f32_e32 v6, 1.0, v6
	v_rcp_f32_e32 v19, v6
	v_lshlrev_b64 v[6:7], 11, v[2:3]
	v_lshl_add_u64 v[6:7], s[94:95], 0, v[6:7]
	v_lshl_add_u64 v[10:11], v[6:7], 0, v[166:167]
	ds_read_b32 v6, v123
	ds_read_b32 v7, v124 offset:256
	s_waitcnt lgkmcnt(0)
	v_pk_mul_f32 v[14:15], v[6:7], v[6:7]
	s_nop 0
	v_mov_b32_e32 v16, v14
	v_mov_b32_e32 v4, v15
	v_pk_add_f32 v[4:5], v[16:17], v[4:5]
	ds_bpermute_b32 v15, v67, v5
	ds_bpermute_b32 v14, v67, v4
	s_waitcnt lgkmcnt(0)
	v_pk_add_f32 v[4:5], v[4:5], v[14:15]
	ds_bpermute_b32 v15, v68, v5
	ds_bpermute_b32 v14, v68, v4
	s_waitcnt lgkmcnt(0)
	v_pk_add_f32 v[4:5], v[4:5], v[14:15]
	ds_bpermute_b32 v15, v56, v5
	ds_bpermute_b32 v14, v56, v4
	s_waitcnt lgkmcnt(0)
	v_pk_add_f32 v[4:5], v[4:5], v[14:15]
	ds_bpermute_b32 v15, v55, v5
	ds_bpermute_b32 v14, v55, v4
	s_waitcnt lgkmcnt(0)
	v_pk_add_f32 v[4:5], v[4:5], v[14:15]
	ds_bpermute_b32 v15, v54, v5
	ds_bpermute_b32 v14, v54, v4
	s_waitcnt lgkmcnt(0)
	v_pk_add_f32 v[4:5], v[4:5], v[14:15]
	ds_bpermute_b32 v15, v53, v5
	ds_bpermute_b32 v14, v53, v4
	s_waitcnt lgkmcnt(0)
	v_pk_add_f32 v[14:15], v[4:5], v[14:15]
	v_mov_b64_e32 v[4:5], s[2:3]
	v_pk_fma_f32 v[14:15], v[14:15], s[16:17], v[4:5] op_sel_hi:[1,0,0]
	s_nop 0
	v_mul_f32_e32 v3, 0x4b800000, v15
	v_cmp_gt_f32_e64 s[78:79], s12, v15
	v_cmp_gt_f32_e32 vcc, s12, v14
	s_nop 0
	v_cndmask_b32_e64 v3, v15, v3, s[78:79]
	v_rsq_f32_e32 v3, v3
	s_nop 0
	v_mul_f32_e32 v15, 0x45800000, v3
	v_cndmask_b32_e64 v3, v3, v15, s[78:79]
	v_mul_f32_e32 v8, v8, v3
	v_mul_f32_e32 v8, v13, v8
	v_mul_f32_e32 v8, v18, v8
	v_mul_f32_e32 v3, v9, v3
	v_mul_f32_e32 v3, v12, v3
	v_bfe_u32 v9, v8, 16, 1
	v_mul_f32_e32 v3, v19, v3
	v_add3_u32 v8, v8, v9, s28
	global_store_short_d16_hi v[10:11], v8, off offset:1024
	v_bfe_u32 v8, v3, 16, 1
	v_add3_u32 v3, v3, v8, s28
	global_store_short_d16_hi v[10:11], v3, off offset:1152
	v_mul_f32_e32 v3, 0x4b800000, v14
	v_cndmask_b32_e32 v3, v14, v3, vcc
	v_rsq_f32_e32 v3, v3
	s_nop 0
	v_mul_f32_e32 v8, 0x45800000, v3
	v_cndmask_b32_e32 v3, v3, v8, vcc
	v_add_u32_e32 v8, 1, v2
	v_mad_i64_i32 v[10:11], s[2:3], v8, s13, v[0:1]
	v_lshl_add_u64 v[10:11], v[10:11], 0, s[30:31]
	v_lshl_add_u64 v[10:11], v[10:11], 0, v[166:167]
	v_lshl_add_u64 v[14:15], v[10:11], 0, s[14:15]
	v_add_co_u32_e32 v10, vcc, s11, v10
	v_mul_f32_e32 v6, v6, v3
	s_nop 0
	v_addc_co_u32_e32 v11, vcc, 0, v11, vcc
	v_mov_b32_e32 v10, v182
	v_mul_f32_e32 v3, v7, v3
	v_mov_b32_e32 v11, v183
	v_mul_f32_e32 v6, v13, v6
	v_mul_f32_e32 v3, v12, v3
	v_ashrrev_i32_e32 v9, 31, v8
	v_lshlrev_b32_e32 v10, 16, v10
	v_mul_f32_e32 v10, 0xbfb8aa3b, v10
	v_lshlrev_b32_e32 v11, 16, v11
	v_exp_f32_e32 v10, v10
	v_mul_f32_e32 v7, 0xbfb8aa3b, v11
	v_exp_f32_e32 v7, v7
	v_add_f32_e32 v10, 1.0, v10
	v_rcp_f32_e32 v10, v10
	v_add_f32_e32 v7, 1.0, v7
	v_rcp_f32_e32 v7, v7
	v_mul_f32_e32 v6, v10, v6
	v_mul_f32_e32 v3, v7, v3
	v_bfe_u32 v7, v6, 16, 1
	v_add3_u32 v10, v6, v7, s28
	v_lshlrev_b64 v[6:7], 11, v[8:9]
	v_lshl_add_u64 v[6:7], s[94:95], 0, v[6:7]
	v_bfe_u32 v8, v3, 16, 1
	v_lshl_add_u64 v[6:7], v[6:7], 0, v[166:167]
	v_add3_u32 v3, v3, v8, s28
	global_store_short_d16_hi v[6:7], v10, off offset:1024
	global_store_short_d16_hi v[6:7], v3, off offset:1152
	v_add_u32_e32 v6, 2, v2
	v_mad_i64_i32 v[14:15], s[2:3], v6, s13, v[0:1]
	v_lshl_add_u64 v[14:15], v[14:15], 0, s[30:31]
	v_lshl_add_u64 v[14:15], v[14:15], 0, v[166:167]
	v_lshl_add_u64 v[16:17], v[14:15], 0, s[14:15]
	v_add_co_u32_e32 v14, vcc, s11, v14
	ds_read_b32 v8, v125
	ds_read_b32 v9, v126 offset:256
	v_addc_co_u32_e32 v15, vcc, 0, v15, vcc
	v_mov_b32_e32 v3, v184
	v_ashrrev_i32_e32 v7, 31, v6
	v_mov_b32_e32 v14, v185
	v_lshlrev_b64 v[6:7], 11, v[6:7]
	v_lshl_add_u64 v[6:7], s[94:95], 0, v[6:7]
	s_waitcnt lgkmcnt(0)
	v_pk_mul_f32 v[10:11], v[8:9], v[8:9]
	v_lshlrev_b32_e32 v3, 16, v3
	v_mov_b32_e32 v19, v10
	v_lshlrev_b32_e32 v14, 16, v14
	v_mul_f32_e32 v14, 0xbfb8aa3b, v14
	v_exp_f32_e32 v14, v14
	v_mul_f32_e32 v3, 0xbfb8aa3b, v3
	v_exp_f32_e32 v3, v3
	v_add_f32_e32 v14, 1.0, v14
	v_rcp_f32_e32 v20, v14
	v_lshl_add_u64 v[14:15], v[6:7], 0, v[166:167]
	ds_read_b32 v6, v127
	ds_read_b32 v7, v128 offset:256
	v_add_f32_e32 v3, 1.0, v3
	v_rcp_f32_e32 v3, v3
	s_waitcnt lgkmcnt(0)
	v_pk_mul_f32 v[16:17], v[6:7], v[6:7]
	s_nop 0
	v_mov_b32_e32 v18, v16
	v_mov_b32_e32 v10, v17
	v_pk_add_f32 v[10:11], v[18:19], v[10:11]
	ds_bpermute_b32 v17, v67, v11
	ds_bpermute_b32 v16, v67, v10
	s_waitcnt lgkmcnt(0)
	v_pk_add_f32 v[10:11], v[10:11], v[16:17]
	ds_bpermute_b32 v17, v68, v11
	ds_bpermute_b32 v16, v68, v10
	s_waitcnt lgkmcnt(0)
	v_pk_add_f32 v[10:11], v[10:11], v[16:17]
	ds_bpermute_b32 v17, v56, v11
	ds_bpermute_b32 v16, v56, v10
	s_waitcnt lgkmcnt(0)
	v_pk_add_f32 v[10:11], v[10:11], v[16:17]
	ds_bpermute_b32 v17, v55, v11
	ds_bpermute_b32 v16, v55, v10
	s_waitcnt lgkmcnt(0)
	v_pk_add_f32 v[10:11], v[10:11], v[16:17]
	ds_bpermute_b32 v17, v54, v11
	ds_bpermute_b32 v16, v54, v10
	s_waitcnt lgkmcnt(0)
	v_pk_add_f32 v[10:11], v[10:11], v[16:17]
	ds_bpermute_b32 v17, v53, v11
	ds_bpermute_b32 v16, v53, v10
	s_waitcnt lgkmcnt(0)
;   __host__ __device__ __forceinline__ bf16_t* ACT() const { return (bf16_t*)(wsl() + OFF_ACT); }
; __device__ __forceinline__ float bf2f(bf16_t h) { return __uint_as_float(((uint32_t)h) << 16); }
; __device__ __forceinline__ float sigmoidf_(float x) { return __builtin_amdgcn_rcpf(1.0f + __expf(-x)); }
; __device__ __forceinline__ void m3_phase(const Params& p, char* smem) {
;     ...
;     for (int q = 0; q < 8; ++q) {
;       int tl = w * 8 + q;
;       float v0 = hs[tl * 132 + lane], v1 = hs[tl * 132 + 64 + lane];
;       float ss = wave_sum(v0 * v0 + v1 * v1);
;       float rstd = rsqrtf(ss * (1.0f / 128.0f) + 1e-6f);
;       int row = rowbase + c * 64 + tl;
;       const bf16_t* po = p.ACT() + (size_t)row * PW + 2208 + h * 128;
;       float o0 = bf2f(po[lane]), o1 = bf2f(po[64 + lane]);
;       float y0 = v0 * rstd * p.mlstm_out_g[h * 128 + lane] * sigmoidf_(o0);
;       float y1 = v1 * rstd * p.mlstm_out_g[h * 128 + 64 + lane] * sigmoidf_(o1);
;       MIX[(size_t)row * D + 512 + h * 128 + lane] = f2bf(y0);
;       MIX[(size_t)row * D + 512 + h * 128 + 64 + lane] = f2bf(y1);
;     }
	v_pk_add_f32 v[10:11], v[10:11], v[16:17]
	s_nop 0
	v_pk_fma_f32 v[10:11], v[10:11], s[16:17], v[4:5] op_sel_hi:[1,0,0]
	s_nop 0
	v_mul_f32_e32 v16, 0x4b800000, v11
	v_cmp_gt_f32_e64 s[78:79], s12, v11
	v_cmp_gt_f32_e32 vcc, s12, v10
	s_nop 0
	v_cndmask_b32_e64 v11, v11, v16, s[78:79]
	v_rsq_f32_e32 v11, v11
	s_nop 0
	v_mul_f32_e32 v16, 0x45800000, v11
	v_cndmask_b32_e64 v11, v11, v16, s[78:79]
	v_mul_f32_e32 v8, v8, v11
	v_mul_f32_e32 v8, v13, v8
	v_mul_f32_e32 v3, v3, v8
	v_mul_f32_e32 v8, v9, v11
	v_mul_f32_e32 v8, v12, v8
	v_bfe_u32 v9, v3, 16, 1
	v_mul_f32_e32 v8, v20, v8
	v_add3_u32 v3, v3, v9, s28
	global_store_short_d16_hi v[14:15], v3, off offset:1024
	v_bfe_u32 v3, v8, 16, 1
	v_add3_u32 v3, v8, v3, s28
	global_store_short_d16_hi v[14:15], v3, off offset:1152
	v_mul_f32_e32 v3, 0x4b800000, v10
	v_cndmask_b32_e32 v3, v10, v3, vcc
	v_rsq_f32_e32 v3, v3
	s_nop 0
	v_mul_f32_e32 v8, 0x45800000, v3
	v_cndmask_b32_e32 v3, v3, v8, vcc
	v_add_u32_e32 v8, 3, v2
	v_mad_i64_i32 v[10:11], s[2:3], v8, s13, v[0:1]
	v_lshl_add_u64 v[10:11], v[10:11], 0, s[30:31]
	v_lshl_add_u64 v[10:11], v[10:11], 0, v[166:167]
	v_lshl_add_u64 v[14:15], v[10:11], 0, s[14:15]
	v_add_co_u32_e32 v10, vcc, s11, v10
	v_mul_f32_e32 v6, v6, v3
	s_nop 0
	v_addc_co_u32_e32 v11, vcc, 0, v11, vcc
	v_mov_b32_e32 v10, v186
	v_mul_f32_e32 v3, v7, v3
	v_mov_b32_e32 v11, v187
	v_mul_f32_e32 v6, v13, v6
	v_mul_f32_e32 v3, v12, v3
	v_ashrrev_i32_e32 v9, 31, v8
	v_lshlrev_b32_e32 v10, 16, v10
	v_mul_f32_e32 v10, 0xbfb8aa3b, v10
	v_lshlrev_b32_e32 v11, 16, v11
	v_exp_f32_e32 v10, v10
	v_mul_f32_e32 v7, 0xbfb8aa3b, v11
	v_exp_f32_e32 v7, v7
	v_add_f32_e32 v10, 1.0, v10
	v_rcp_f32_e32 v10, v10
	v_add_f32_e32 v7, 1.0, v7
	v_rcp_f32_e32 v7, v7
	v_mul_f32_e32 v6, v10, v6
	v_mul_f32_e32 v3, v7, v3
	v_bfe_u32 v7, v6, 16, 1
	v_add3_u32 v10, v6, v7, s28
	v_lshlrev_b64 v[6:7], 11, v[8:9]
	v_lshl_add_u64 v[6:7], s[94:95], 0, v[6:7]
	v_lshl_add_u64 v[6:7], v[6:7], 0, v[166:167]
	global_store_short_d16_hi v[6:7], v10, off offset:1024
	v_add_u32_e32 v10, 4, v2
	v_mad_i64_i32 v[14:15], s[2:3], v10, s13, v[0:1]
	v_lshl_add_u64 v[14:15], v[14:15], 0, s[30:31]
	v_bfe_u32 v8, v3, 16, 1
	v_lshl_add_u64 v[14:15], v[14:15], 0, v[166:167]
	v_add3_u32 v3, v3, v8, s28
	v_lshl_add_u64 v[16:17], v[14:15], 0, s[14:15]
	v_add_co_u32_e32 v14, vcc, s11, v14
	global_store_short_d16_hi v[6:7], v3, off offset:1152
	s_nop 0
	v_addc_co_u32_e32 v15, vcc, 0, v15, vcc
	ds_read_b32 v6, v129
	ds_read_b32 v7, v130 offset:256
	v_mov_b32_e32 v3, v188
	v_ashrrev_i32_e32 v11, 31, v10
	v_mov_b32_e32 v14, v189
	v_lshlrev_b64 v[10:11], 11, v[10:11]
	v_lshl_add_u64 v[10:11], s[94:95], 0, v[10:11]
	s_waitcnt lgkmcnt(0)
	v_pk_mul_f32 v[8:9], v[6:7], v[6:7]
	v_lshlrev_b32_e32 v3, 16, v3
	v_mov_b32_e32 v19, v8
	v_lshlrev_b32_e32 v14, 16, v14
	v_mul_f32_e32 v14, 0xbfb8aa3b, v14
	v_exp_f32_e32 v14, v14
	v_mul_f32_e32 v3, 0xbfb8aa3b, v3
	v_exp_f32_e32 v3, v3
	v_add_f32_e32 v14, 1.0, v14
	v_rcp_f32_e32 v20, v14
	v_lshl_add_u64 v[14:15], v[10:11], 0, v[166:167]
	ds_read_b32 v10, v131
	ds_read_b32 v11, v132 offset:256
	v_add_f32_e32 v3, 1.0, v3
	v_rcp_f32_e32 v3, v3
	s_waitcnt lgkmcnt(0)
	v_pk_mul_f32 v[16:17], v[10:11], v[10:11]
	s_nop 0
	v_mov_b32_e32 v18, v16
	v_mov_b32_e32 v8, v17
	v_pk_add_f32 v[8:9], v[18:19], v[8:9]
	ds_bpermute_b32 v17, v67, v9
	ds_bpermute_b32 v16, v67, v8
	s_waitcnt lgkmcnt(0)
	v_pk_add_f32 v[8:9], v[8:9], v[16:17]
	ds_bpermute_b32 v17, v68, v9
	ds_bpermute_b32 v16, v68, v8
	s_waitcnt lgkmcnt(0)
	v_pk_add_f32 v[8:9], v[8:9], v[16:17]
	ds_bpermute_b32 v17, v56, v9
	ds_bpermute_b32 v16, v56, v8
	s_waitcnt lgkmcnt(0)
	v_pk_add_f32 v[8:9], v[8:9], v[16:17]
	ds_bpermute_b32 v17, v55, v9
	ds_bpermute_b32 v16, v55, v8
	s_waitcnt lgkmcnt(0)
	v_pk_add_f32 v[8:9], v[8:9], v[16:17]
	ds_bpermute_b32 v17, v54, v9
	ds_bpermute_b32 v16, v54, v8
	s_waitcnt lgkmcnt(0)
	v_pk_add_f32 v[8:9], v[8:9], v[16:17]
	ds_bpermute_b32 v17, v53, v9
	ds_bpermute_b32 v16, v53, v8
	s_waitcnt lgkmcnt(0)
;   __host__ __device__ __forceinline__ bf16_t* ACT() const { return (bf16_t*)(wsl() + OFF_ACT); }
; __device__ __forceinline__ float bf2f(bf16_t h) { return __uint_as_float(((uint32_t)h) << 16); }
; __device__ __forceinline__ float sigmoidf_(float x) { return __builtin_amdgcn_rcpf(1.0f + __expf(-x)); }
; __device__ __forceinline__ void m3_phase(const Params& p, char* smem) {
;     ...
;     for (int q = 0; q < 8; ++q) {
;       int tl = w * 8 + q;
;       float v0 = hs[tl * 132 + lane], v1 = hs[tl * 132 + 64 + lane];
;       float ss = wave_sum(v0 * v0 + v1 * v1);
;       float rstd = rsqrtf(ss * (1.0f / 128.0f) + 1e-6f);
;       int row = rowbase + c * 64 + tl;
;       const bf16_t* po = p.ACT() + (size_t)row * PW + 2208 + h * 128;
;       float o0 = bf2f(po[lane]), o1 = bf2f(po[64 + lane]);
;       float y0 = v0 * rstd * p.mlstm_out_g[h * 128 + lane] * sigmoidf_(o0);
;       float y1 = v1 * rstd * p.mlstm_out_g[h * 128 + 64 + lane] * sigmoidf_(o1);
;       MIX[(size_t)row * D + 512 + h * 128 + lane] = f2bf(y0);
;       MIX[(size_t)row * D + 512 + h * 128 + 64 + lane] = f2bf(y1);
;     }
;     __syncthreads();
;   }
	v_pk_add_f32 v[8:9], v[8:9], v[16:17]
	s_nop 0
	v_pk_fma_f32 v[8:9], v[8:9], s[16:17], v[4:5] op_sel_hi:[1,0,0]
	s_nop 0
	v_mul_f32_e32 v16, 0x4b800000, v9
	v_cmp_gt_f32_e64 s[78:79], s12, v9
	v_cmp_gt_f32_e32 vcc, s12, v8
	s_nop 0
	v_cndmask_b32_e64 v9, v9, v16, s[78:79]
	v_rsq_f32_e32 v9, v9
	s_nop 0
	v_mul_f32_e32 v16, 0x45800000, v9
	v_cndmask_b32_e64 v9, v9, v16, s[78:79]
	v_mul_f32_e32 v6, v6, v9
	v_mul_f32_e32 v6, v13, v6
	v_mul_f32_e32 v3, v3, v6
	v_mul_f32_e32 v6, v7, v9
	v_mul_f32_e32 v6, v12, v6
	v_bfe_u32 v7, v3, 16, 1
	v_mul_f32_e32 v6, v20, v6
	v_add3_u32 v3, v3, v7, s28
	global_store_short_d16_hi v[14:15], v3, off offset:1024
	v_bfe_u32 v3, v6, 16, 1
	v_add3_u32 v3, v6, v3, s28
	global_store_short_d16_hi v[14:15], v3, off offset:1152
	v_mul_f32_e32 v3, 0x4b800000, v8
	v_cndmask_b32_e32 v3, v8, v3, vcc
	v_rsq_f32_e32 v3, v3
	s_nop 0
	v_mul_f32_e32 v6, 0x45800000, v3
	v_cndmask_b32_e32 v3, v3, v6, vcc
	v_add_u32_e32 v6, 5, v2
	v_mad_i64_i32 v[8:9], s[2:3], v6, s13, v[0:1]
	v_lshl_add_u64 v[8:9], v[8:9], 0, s[30:31]
	v_lshl_add_u64 v[8:9], v[8:9], 0, v[166:167]
	v_lshl_add_u64 v[14:15], v[8:9], 0, s[14:15]
	v_add_co_u32_e32 v8, vcc, s11, v8
	v_mul_f32_e32 v10, v10, v3
	s_nop 0
	v_addc_co_u32_e32 v9, vcc, 0, v9, vcc
	v_mov_b32_e32 v8, v190
	v_ashrrev_i32_e32 v7, 31, v6
	v_mov_b32_e32 v9, v191
	v_mul_f32_e32 v10, v13, v10
	v_mul_f32_e32 v3, v11, v3
	v_mul_f32_e32 v3, v12, v3
	v_lshlrev_b64 v[6:7], 11, v[6:7]
	v_lshl_add_u64 v[6:7], s[94:95], 0, v[6:7]
	v_lshl_add_u64 v[6:7], v[6:7], 0, v[166:167]
	v_lshlrev_b32_e32 v8, 16, v8
	v_mul_f32_e32 v8, 0xbfb8aa3b, v8
	v_lshlrev_b32_e32 v9, 16, v9
	v_exp_f32_e32 v8, v8
	v_mul_f32_e32 v9, 0xbfb8aa3b, v9
	v_exp_f32_e32 v9, v9
	v_add_f32_e32 v8, 1.0, v8
	v_rcp_f32_e32 v8, v8
	v_add_f32_e32 v9, 1.0, v9
	v_rcp_f32_e32 v9, v9
	v_mul_f32_e32 v8, v8, v10
	v_mul_f32_e32 v3, v9, v3
	v_bfe_u32 v9, v8, 16, 1
	v_add3_u32 v8, v8, v9, s28
	global_store_short_d16_hi v[6:7], v8, off offset:1024
	v_bfe_u32 v8, v3, 16, 1
	v_add3_u32 v3, v3, v8, s28
	global_store_short_d16_hi v[6:7], v3, off offset:1152
	v_add_u32_e32 v6, 6, v2
	v_mad_i64_i32 v[14:15], s[2:3], v6, s13, v[0:1]
	v_lshl_add_u64 v[14:15], v[14:15], 0, s[30:31]
	v_lshl_add_u64 v[14:15], v[14:15], 0, v[166:167]
	v_lshl_add_u64 v[16:17], v[14:15], 0, s[14:15]
	v_add_co_u32_e32 v14, vcc, s11, v14
	ds_read_b32 v8, v133
	ds_read_b32 v9, v134 offset:256
	v_addc_co_u32_e32 v15, vcc, 0, v15, vcc
	v_mov_b32_e32 v3, v192
	v_ashrrev_i32_e32 v7, 31, v6
	v_mov_b32_e32 v14, v193
	v_lshlrev_b64 v[6:7], 11, v[6:7]
	v_lshl_add_u64 v[6:7], s[94:95], 0, v[6:7]
	s_waitcnt lgkmcnt(0)
	v_pk_mul_f32 v[10:11], v[8:9], v[8:9]
	v_add_u32_e32 v2, 7, v2
	v_mov_b32_e32 v19, v10
	v_mad_i64_i32 v[0:1], s[2:3], v2, s13, v[0:1]
	v_lshl_add_u64 v[0:1], v[0:1], 0, s[30:31]
	v_lshl_add_u64 v[0:1], v[0:1], 0, v[166:167]
	v_readlane_b32 s2, v255, 28
	v_lshlrev_b32_e32 v3, 16, v3
	v_mul_f32_e32 v3, 0xbfb8aa3b, v3
	v_lshlrev_b32_e32 v14, 16, v14
	v_mul_f32_e32 v14, 0xbfb8aa3b, v14
	v_exp_f32_e32 v14, v14
	v_exp_f32_e32 v3, v3
	v_add_u32_e32 v145, s2, v145
	v_add_u32_e32 v66, s2, v66
	v_add_f32_e32 v14, 1.0, v14
	v_rcp_f32_e32 v20, v14
	v_lshl_add_u64 v[14:15], v[6:7], 0, v[166:167]
	ds_read_b32 v6, v135
	ds_read_b32 v7, v136 offset:256
	v_add_f32_e32 v3, 1.0, v3
	v_rcp_f32_e32 v3, v3
	v_add_u32_e32 v144, s2, v144
	s_waitcnt lgkmcnt(0)
	v_pk_mul_f32 v[16:17], v[6:7], v[6:7]
	s_nop 0
	v_mov_b32_e32 v18, v16
	v_mov_b32_e32 v10, v17
	v_pk_add_f32 v[10:11], v[18:19], v[10:11]
	ds_bpermute_b32 v17, v67, v11
	ds_bpermute_b32 v16, v67, v10
	s_waitcnt lgkmcnt(0)
	v_pk_add_f32 v[10:11], v[10:11], v[16:17]
	ds_bpermute_b32 v17, v68, v11
	ds_bpermute_b32 v16, v68, v10
	s_waitcnt lgkmcnt(0)
	v_pk_add_f32 v[10:11], v[10:11], v[16:17]
	ds_bpermute_b32 v17, v56, v11
	ds_bpermute_b32 v16, v56, v10
	s_waitcnt lgkmcnt(0)
	v_pk_add_f32 v[10:11], v[10:11], v[16:17]
	ds_bpermute_b32 v17, v55, v11
	ds_bpermute_b32 v16, v55, v10
	s_waitcnt lgkmcnt(0)
	v_pk_add_f32 v[10:11], v[10:11], v[16:17]
	ds_bpermute_b32 v17, v54, v11
	ds_bpermute_b32 v16, v54, v10
	s_waitcnt lgkmcnt(0)
	v_pk_add_f32 v[10:11], v[10:11], v[16:17]
	ds_bpermute_b32 v17, v53, v11
	ds_bpermute_b32 v16, v53, v10
	s_waitcnt lgkmcnt(0)
	v_pk_add_f32 v[10:11], v[10:11], v[16:17]
	s_nop 0
	v_pk_fma_f32 v[4:5], v[10:11], s[16:17], v[4:5] op_sel_hi:[1,0,0]
	s_nop 0
	v_mul_f32_e32 v10, 0x4b800000, v5
	v_cmp_gt_f32_e64 s[78:79], s12, v5
	v_cmp_gt_f32_e32 vcc, s12, v4
	s_nop 0
	v_cndmask_b32_e64 v5, v5, v10, s[78:79]
	v_rsq_f32_e32 v5, v5
	s_nop 0
	v_mul_f32_e32 v10, 0x45800000, v5
	v_cndmask_b32_e64 v5, v5, v10, s[78:79]
	v_mul_f32_e32 v8, v8, v5
	v_mul_f32_e32 v8, v13, v8
	v_mul_f32_e32 v3, v3, v8
	v_mul_f32_e32 v5, v9, v5
	v_mul_f32_e32 v5, v12, v5
	v_bfe_u32 v8, v3, 16, 1
	v_mul_f32_e32 v5, v20, v5
	v_add3_u32 v3, v3, v8, s28
	global_store_short_d16_hi v[14:15], v3, off offset:1024
	v_bfe_u32 v3, v5, 16, 1
	v_add3_u32 v3, v5, v3, s28
	global_store_short_d16_hi v[14:15], v3, off offset:1152
	v_mul_f32_e32 v3, 0x4b800000, v4
	v_cndmask_b32_e32 v3, v4, v3, vcc
	v_rsq_f32_e32 v3, v3
	v_lshl_add_u64 v[8:9], v[0:1], 0, s[14:15]
	v_mul_f32_e32 v4, 0x45800000, v3
	v_cndmask_b32_e32 v4, v3, v4, vcc
	v_add_co_u32_e32 v0, vcc, s11, v0
	v_mul_f32_e32 v5, v6, v4
	s_nop 0
	v_addc_co_u32_e32 v1, vcc, 0, v1, vcc
	v_mov_b32_e32 v0, v194
	v_mul_f32_e32 v5, v13, v5
	v_mov_b32_e32 v1, v195
	v_mul_f32_e32 v4, v7, v4
	v_mul_f32_e32 v4, v12, v4
	v_ashrrev_i32_e32 v3, 31, v2
	v_lshlrev_b32_e32 v0, 16, v0
	v_mul_f32_e32 v0, 0xbfb8aa3b, v0
	v_lshlrev_b32_e32 v1, 16, v1
	v_exp_f32_e32 v0, v0
	v_mul_f32_e32 v1, 0xbfb8aa3b, v1
	v_exp_f32_e32 v1, v1
	v_add_f32_e32 v0, 1.0, v0
	v_rcp_f32_e32 v0, v0
	v_add_f32_e32 v1, 1.0, v1
	v_rcp_f32_e32 v1, v1
	v_mul_f32_e32 v0, v0, v5
	v_mul_f32_e32 v4, v1, v4
	v_bfe_u32 v1, v0, 16, 1
	v_add3_u32 v5, v0, v1, s28
	v_lshlrev_b64 v[0:1], 11, v[2:3]
	v_lshl_add_u64 v[0:1], s[94:95], 0, v[0:1]
	v_bfe_u32 v2, v4, 16, 1
	v_lshl_add_u64 v[0:1], v[0:1], 0, v[166:167]
	v_add3_u32 v2, v4, v2, s28
	global_store_short_d16_hi v[0:1], v5, off offset:1024
	global_store_short_d16_hi v[0:1], v2, off offset:1152
	s_barrier
	s_cbranch_scc1 .LBB0_549

;   __host__ __device__ __forceinline__ bf16_t* ACT() const { return (bf16_t*)(wsl() + OFF_ACT); }
;   __host__ __device__ __forceinline__ bf16_t* R() const { return (bf16_t*)(wsl() + OFF_R); }
; #define MFMA16(a, b, c) __builtin_amdgcn_mfma_f32_16x16x32_bf16(a, b, c, 0, 0, 0)
; __device__ __forceinline__ void m3_phase(const Params& p, char* smem) {
;     ...
;       for (int i = 0; i < 2; ++i) {
;         int idx = tid + i * NTHR;
;         int r = idx & 63, fc = (idx >> 6) * 8;
;         int row = rowbase + mchunk_tok(dir, j, r);
;         const bf16_t* src = p.ACT() + (size_t)row * PW;
;         uint4 qv = *(const uint4*)(src + 672 + h * 128 + fc);
;         uint4 kv = *(const uint4*)(src + 1184 + h * 128 + fc);
;         uint4 vv = *(const uint4*)(src + 1696 + h * 128 + fc);
;         *(uint4*)(Qs + r * 136 + fc) = qv;
;         *(uint4*)(Ks + r * 136 + fc) = kv;
;         const bf16_t* ve = (const bf16_t*)&vv;
; #pragma unroll
;         for (int e = 0; e < 8; ++e) Vt[(fc + e) * 72 + r] = ve[e];
;       }
;       {
;         const bf16_t* cst = p.R() + (size_t)sidx * 16384;
; #pragma unroll
;         for (int i = 0; i < 4; ++i) {
;           int idx = tid + i * NTHR;
;           int v = idx >> 4, kc = (idx & 15) * 8;
;           *(uint4*)(Cs + v * 136 + kc) = *(const uint4*)(cst + v * 128 + kc);
;         }
;       }
;       __syncthreads();
;       {
;         const int mi = w & 3, nb2 = (w >> 2) * 2;
;         f32x4 s2[2] = {(f32x4){0.f, 0.f, 0.f, 0.f}, (f32x4){0.f, 0.f, 0.f, 0.f}};
; #pragma unroll
;         for (int ks = 0; ks < 4; ++ks) {
;           bf16x8 a = *(const bf16x8*)(Qs + (mi * 16 + fr) * 136 + ks * 32 + fq * 8);
; #pragma unroll
;           for (int q = 0; q < 2; ++q) {
;             bf16x8 bb = *(const bf16x8*)(Ks + ((nb2 + q) * 16 + fr) * 136 + ks * 32 + fq * 8);
;             s2[q] = MFMA16(a, bb, s2[q]);
;           }
;         }
.LBB0_491:
	s_or_b64 exec, exec, s[2:3]
	s_sub_i32 s11, s12, s11
	s_add_i32 s11, s11, s9
	v_add_u32_e32 v4, s11, v144
	v_mov_b64_e32 v[2:3], s[90:91]
	v_mad_i64_i32 v[2:3], s[2:3], v4, s84, v[2:3]
	s_lshl_b32 s30, s13, 8
	v_lshl_add_u64 v[14:15], v[2:3], 0, s[30:31]
	v_lshl_add_u64 v[10:11], v[14:15], 0, v[196:197]
	global_load_dwordx4 v[2:5], v[10:11], off offset:1344
	global_load_dwordx4 v[6:9], v[10:11], off offset:2368
	s_nop 0
	global_load_dwordx4 v[10:13], v[10:11], off offset:3392
	v_lshlrev_b64 v[0:1], 15, v[0:1]
	s_waitcnt vmcnt(2)
	ds_write_b128 v178, v[2:5]
	s_waitcnt vmcnt(1)
	ds_write_b128 v178, v[6:9] offset:17408
	s_waitcnt vmcnt(0)
	ds_write_b128 v171, v[10:13] offset:34816
	v_lshl_add_u64 v[10:11], v[14:15], 0, v[198:199]
	global_load_dwordx4 v[2:5], v[10:11], off offset:1344
	global_load_dwordx4 v[6:9], v[10:11], off offset:2368
	s_nop 0
	global_load_dwordx4 v[10:13], v[10:11], off offset:3392
	s_waitcnt vmcnt(2)
	ds_write_b128 v178, v[2:5] offset:8704
	s_waitcnt vmcnt(1)
	ds_write_b128 v178, v[6:9] offset:26112
	s_waitcnt vmcnt(0)
	ds_write_b128 v171, v[10:13] offset:44032
	v_lshl_add_u64 v[4:5], v[48:49], 0, v[0:1]
	v_lshl_add_u64 v[0:1], v[40:41], 1, v[4:5]
	global_load_dwordx4 v[0:3], v[0:1], off
	s_waitcnt vmcnt(0)
	ds_write_b128 v78, v[0:3]
	v_lshl_add_u64 v[0:1], v[42:43], 1, v[4:5]
	global_load_dwordx4 v[0:3], v[0:1], off
	s_waitcnt vmcnt(0)
	ds_write_b128 v79, v[0:3]
	v_lshl_add_u64 v[0:1], v[44:45], 1, v[4:5]
	global_load_dwordx4 v[0:3], v[0:1], off
	s_waitcnt vmcnt(0)
	ds_write_b128 v80, v[0:3]
	v_lshl_add_u64 v[0:1], v[46:47], 1, v[4:5]
	global_load_dwordx4 v[0:3], v[0:1], off
	s_waitcnt vmcnt(0)
	ds_write_b128 v81, v[0:3]
	s_waitcnt lgkmcnt(0)
	s_barrier
	ds_read_b128 v[160:163], v52
	ds_read_b128 v[172:175], v140 offset:17408
	ds_read_b128 v[204:207], v140 offset:21760
	ds_read_b128 v[208:211], v52 offset:64
	ds_read_b128 v[212:215], v140 offset:17472
	ds_read_b128 v[236:239], v140 offset:21824
	ds_read_b128 v[240:243], v52 offset:128
	ds_read_b128 v[244:247], v140 offset:17536
	s_waitcnt lgkmcnt(6)
	v_mfma_f32_16x16x32_bf16 v[4:7], v[160:163], v[172:175], 0
	ds_read_b128 v[248:251], v140 offset:21888
	s_waitcnt lgkmcnt(6)
	v_mfma_f32_16x16x32_bf16 v[0:3], v[160:163], v[204:207], 0
	ds_read_b128 v[172:175], v52 offset:192
	ds_read_b128 v[160:163], v140 offset:17600
	s_waitcnt lgkmcnt(6)
	v_mfma_f32_16x16x32_bf16 v[4:7], v[208:211], v[212:215], v[4:7]
	ds_read_b128 v[204:207], v140 offset:21952
	s_waitcnt lgkmcnt(6)
	v_mfma_f32_16x16x32_bf16 v[0:3], v[208:211], v[236:239], v[0:3]
	s_waitcnt lgkmcnt(4)
	v_mfma_f32_16x16x32_bf16 v[4:7], v[240:243], v[244:247], v[4:7]
	s_waitcnt lgkmcnt(3)
	v_mfma_f32_16x16x32_bf16 v[0:3], v[240:243], v[248:251], v[0:3]
	s_waitcnt lgkmcnt(1)
	v_mfma_f32_16x16x32_bf16 v[4:7], v[172:175], v[160:163], v[4:7]
	s_waitcnt lgkmcnt(0)
	v_mfma_f32_16x16x32_bf16 v[0:3], v[172:175], v[204:207], v[0:3]
	ds_read_b32 v10, v82
	v_mov_b32_e32 v11, 0
	v_mov_b32_e32 v8, 0
	s_and_saveexec_b64 s[2:3], s[60:61]
	s_cbranch_execz .LBB0_493
	ds_read_b32 v8, v84
	s_waitcnt lgkmcnt(0)
	v_add_f32_e32 v8, v10, v8
	v_mul_f32_e32 v8, 0x3fb8aa3b, v8
	v_exp_f32_e32 v8, v8

; #define MFMA16(a, b, c) __builtin_amdgcn_mfma_f32_16x16x32_bf16(a, b, c, 0, 0, 0)
; __device__ __forceinline__ void m3_phase(const Params& p, char* smem) {
;     ...
;       {
;         const int mi = w & 3, nh = w >> 2;
;         f32x4 a1[4], a2[4];
; #pragma unroll
;         for (int q = 0; q < 4; ++q) { a1[q] = (f32x4){0.f, 0.f, 0.f, 0.f}; a2[q] = (f32x4){0.f, 0.f, 0.f, 0.f}; }
; #pragma unroll
;         for (int ks = 0; ks < 2; ++ks) {
;           bf16x8 a = *(const bf16x8*)(Sw + (mi * 16 + fr) * 72 + ks * 32 + fq * 8);
; #pragma unroll
;           for (int q = 0; q < 4; ++q) {
;             bf16x8 bb = *(const bf16x8*)(Vt + ((nh * 4 + q) * 16 + fr) * 72 + ks * 32 + fq * 8);
;             a1[q] = MFMA16(a, bb, a1[q]);
;           }
;         }
; #pragma unroll
;         for (int ks = 0; ks < 4; ++ks) {
;           bf16x8 a = *(const bf16x8*)(Qs + (mi * 16 + fr) * 136 + ks * 32 + fq * 8);
; #pragma unroll
;           for (int q = 0; q < 4; ++q) {
;             bf16x8 bb = *(const bf16x8*)(Cs + ((nh * 4 + q) * 16 + fr) * 136 + ks * 32 + fq * 8);
;             a2[q] = MFMA16(a, bb, a2[q]);
;           }
;         }
; #pragma unroll
;         for (int jj = 0; jj < 4; ++jj) {
;           int t = mi * 16 + fq * 4 + jj;
;           float wi = wint[t];
;           float den = denp[t] + denp[64 + t] + wi * qn[t];
;           float inv = 1.0f / fmaxf(fabsf(den), emt[t]);
;           int tl = (dir == 0) ? t : (63 - t);
; #pragma unroll
;           for (int q = 0; q < 4; ++q) {
;             int v = (nh * 4 + q) * 16 + fr;
;             float hv = (a1[q][jj] + wi * a2[q][jj]) * inv;
;             if (dir == 0) hs[tl * 132 + v] = hv; else hs[tl * 132 + v] += hv;
;           }
;         }
.LBB0_517:
	s_or_b64 exec, exec, s[2:3]
	s_waitcnt lgkmcnt(0)
	s_barrier
	v_add_u32_e32 v150, v35, v97
	s_mul_i32 s2, s15, 0xffffff7c
	s_add_i32 s2, s4, s2
	s_cmp_gt_i32 s2, 3
	s_cselect_b32 s16, 0x87, 3
	s_add_i32 s2, s16, s14
	s_add_i32 s2, s10, s2
	s_cmp_gt_i32 s2, 3
	s_mulk_i32 s15, 0x18c
	s_cselect_b32 s17, 0x87, 3
	ds_read_b128 v[160:163], v59
	ds_read_b64_tr_b16 v[172:173], v179 offset:34816
	ds_read_b64_tr_b16 v[174:175], v179 offset:35968
	ds_read_b64_tr_b16 v[204:205], v179 offset:34848
	ds_read_b64_tr_b16 v[206:207], v179 offset:36000
	ds_read_b64_tr_b16 v[208:209], v179 offset:34880
	ds_read_b64_tr_b16 v[210:211], v179 offset:36032
	ds_read_b64_tr_b16 v[212:213], v179 offset:34912
	ds_read_b64_tr_b16 v[214:215], v179 offset:36064
	ds_read_b128 v[236:239], v59 offset:64
	ds_read_b64_tr_b16 v[240:241], v179 offset:44032
	ds_read_b64_tr_b16 v[242:243], v179 offset:45184
	s_waitcnt lgkmcnt(5)
	v_mfma_f32_16x16x32_bf16 v[16:19], v[160:163], v[208:211], 0
	ds_read_b128 v[244:247], v150 offset:57600
	ds_read_b128 v[248:251], v150 offset:61952
	v_mfma_f32_16x16x32_bf16 v[4:7], v[160:163], v[172:175], 0
	ds_read_b64_tr_b16 v[208:209], v179 offset:44064
	ds_read_b64_tr_b16 v[210:211], v179 offset:45216
	v_mfma_f32_16x16x32_bf16 v[8:11], v[160:163], v[204:207], 0
	ds_read_b128 v[172:175], v143 offset:61952
	s_waitcnt lgkmcnt(8)
	v_mfma_f32_16x16x32_bf16 v[0:3], v[160:163], v[212:215], 0
	ds_read_b64_tr_b16 v[204:205], v179 offset:44096
	ds_read_b64_tr_b16 v[206:207], v179 offset:45248
	ds_read_b64_tr_b16 v[160:161], v179 offset:44128
	ds_read_b64_tr_b16 v[162:163], v179 offset:45280
	s_waitcnt lgkmcnt(9)
	v_mfma_f32_16x16x32_bf16 v[12:15], v[236:239], v[240:243], v[4:7]
	ds_read_b128 v[212:215], v52
	s_waitcnt lgkmcnt(6)
	v_mfma_f32_16x16x32_bf16 v[8:11], v[236:239], v[208:211], v[8:11]
	ds_read_b128 v[240:243], v150 offset:53248
	s_waitcnt lgkmcnt(4)
	v_mfma_f32_16x16x32_bf16 v[4:7], v[236:239], v[204:207], v[16:19]
	ds_read_b128 v[208:211], v52 offset:64
	s_waitcnt lgkmcnt(3)
	v_mfma_f32_16x16x32_bf16 v[0:3], v[236:239], v[160:163], v[0:3]
	ds_read_b128 v[204:207], v150 offset:53312
	ds_read_b128 v[236:239], v150 offset:57664
	s_waitcnt lgkmcnt(3)
	v_mfma_f32_16x16x32_bf16 v[20:23], v[212:215], v[240:243], 0
	ds_read_b128 v[160:163], v150 offset:62016
	v_mfma_f32_16x16x32_bf16 v[24:27], v[212:215], v[244:247], 0
	ds_read_b128 v[240:243], v143 offset:62016
	v_mfma_f32_16x16x32_bf16 v[28:31], v[212:215], v[248:251], 0
	ds_read_b128 v[244:247], v52 offset:128
	v_mfma_f32_16x16x32_bf16 v[16:19], v[212:215], v[172:175], 0
	ds_read_b128 v[248:251], v150 offset:53376
	ds_read_b128 v[212:215], v150 offset:57728
	s_waitcnt lgkmcnt(6)
	v_mfma_f32_16x16x32_bf16 v[20:23], v[208:211], v[204:207], v[20:23]
	ds_read_b128 v[172:175], v150 offset:62080
	s_waitcnt lgkmcnt(6)
	v_mfma_f32_16x16x32_bf16 v[24:27], v[208:211], v[236:239], v[24:27]
	ds_read_b128 v[204:207], v143 offset:62080
	s_waitcnt lgkmcnt(6)
	v_mfma_f32_16x16x32_bf16 v[28:31], v[208:211], v[160:163], v[28:31]
	ds_read_b128 v[236:239], v52 offset:192
	s_waitcnt lgkmcnt(6)
	v_mfma_f32_16x16x32_bf16 v[16:19], v[208:211], v[240:243], v[16:19]
	ds_read_b128 v[160:163], v150 offset:53440
	ds_read_b128 v[208:211], v150 offset:57792
	s_waitcnt lgkmcnt(6)
	v_mfma_f32_16x16x32_bf16 v[20:23], v[244:247], v[248:251], v[20:23]
	ds_read_b128 v[240:243], v150 offset:62144
	s_waitcnt lgkmcnt(6)
	v_mfma_f32_16x16x32_bf16 v[24:27], v[244:247], v[212:215], v[24:27]
	ds_read_b128 v[248:251], v143 offset:62144
	s_waitcnt lgkmcnt(6)
	v_mfma_f32_16x16x32_bf16 v[156:159], v[244:247], v[172:175], v[28:31]
	s_waitcnt lgkmcnt(5)
	v_mfma_f32_16x16x32_bf16 v[16:19], v[244:247], v[204:207], v[16:19]
	s_waitcnt lgkmcnt(3)
	v_mfma_f32_16x16x32_bf16 v[28:31], v[236:239], v[160:163], v[20:23]
	s_waitcnt lgkmcnt(2)
	v_mfma_f32_16x16x32_bf16 v[24:27], v[236:239], v[208:211], v[24:27]
	s_waitcnt lgkmcnt(1)
	v_mfma_f32_16x16x32_bf16 v[20:23], v[236:239], v[240:243], v[156:159]
	s_waitcnt lgkmcnt(0)
	v_mfma_f32_16x16x32_bf16 v[16:19], v[236:239], v[248:251], v[16:19]
	ds_read_b32 v151, v98
	ds_read2st64_b32 v[152:153], v99 offset1:1
	s_waitcnt lgkmcnt(1)
	v_fma_f32 v12, v28, v151, v12
	s_waitcnt lgkmcnt(0)
	v_add_f32_e32 v152, v152, v153
	ds_read_b32 v153, v100
	v_fma_f32 v8, v24, v151, v8
	v_fma_f32 v4, v20, v151, v4
	v_fma_f32 v0, v151, v16, v0
	s_waitcnt lgkmcnt(0)
	v_fmac_f32_e32 v152, v151, v153
	ds_read_b32 v153, v101
	s_waitcnt lgkmcnt(0)
	v_max_f32_e32 v153, v153, v153
	v_max_f32_e64 v152, |v152|, v153
	v_div_scale_f32 v153, s[2:3], v152, v152, 1.0
	v_rcp_f32_e32 v154, v153
	s_nop 0
	v_fma_f32 v155, -v153, v154, 1.0
	v_fmac_f32_e32 v154, v155, v154
	v_div_scale_f32 v155, vcc, 1.0, v152, 1.0
	v_mul_f32_e32 v156, v155, v154
	v_fma_f32 v157, -v153, v156, v155
	v_fmac_f32_e32 v156, v157, v154
	v_fma_f32 v153, -v153, v156, v155
	v_div_fmas_f32 v153, v153, v154, v156
	v_div_fixup_f32 v152, v153, v152, 1.0
	v_mul_f32_e32 v12, v12, v152
	v_mul_f32_e32 v8, v8, v152
	v_mul_f32_e32 v4, v4, v152
	v_mul_f32_e32 v0, v0, v152
	ds_write2_b32 v102, v12, v8 offset1:16
	ds_write2_b32 v102, v4, v0 offset0:32 offset1:48
	ds_read_b32 v0, v103
	ds_read_b32 v4, v104
	ds_read_b32 v8, v105
	ds_read2st64_b32 v[152:153], v106 offset1:1
	s_waitcnt lgkmcnt(3)
	v_fma_f32 v9, v25, v0, v9
	s_waitcnt lgkmcnt(2)
	v_max_f32_e32 v4, v4, v4
	v_fma_f32 v5, v21, v0, v5
	s_waitcnt lgkmcnt(0)
; __device__ __forceinline__ void m3_phase(const Params& p, char* smem) {
;     ...
; #pragma unroll
;         for (int jj = 0; jj < 4; ++jj) {
;           int t = mi * 16 + fq * 4 + jj;
;           float wi = wint[t];
;           float den = denp[t] + denp[64 + t] + wi * qn[t];
;           float inv = 1.0f / fmaxf(fabsf(den), emt[t]);
;           int tl = (dir == 0) ? t : (63 - t);
; #pragma unroll
;           for (int q = 0; q < 4; ++q) {
;             int v = (nh * 4 + q) * 16 + fr;
;             float hv = (a1[q][jj] + wi * a2[q][jj]) * inv;
;             if (dir == 0) hs[tl * 132 + v] = hv; else hs[tl * 132 + v] += hv;
;           }
;         }
;       }
;       __syncthreads();
	v_add_f32_e32 v12, v153, v152
	v_fmac_f32_e32 v12, v0, v8
	v_max_f32_e64 v4, |v12|, v4
	v_div_scale_f32 v8, s[2:3], v4, v4, 1.0
	v_rcp_f32_e32 v12, v8
	s_nop 0
	v_fma_f32 v16, -v8, v12, 1.0
	v_fmac_f32_e32 v12, v16, v12
	v_div_scale_f32 v16, vcc, 1.0, v4, 1.0
	v_mul_f32_e32 v20, v16, v12
	v_fma_f32 v24, -v8, v20, v16
	v_fmac_f32_e32 v20, v24, v12
	v_fma_f32 v8, -v8, v20, v16
	v_div_fmas_f32 v8, v8, v12, v20
	v_div_fixup_f32 v4, v8, v4, 1.0
	v_fma_f32 v8, v29, v0, v13
	v_fma_f32 v0, v17, v0, v1
	v_mul_f32_e32 v8, v8, v4
	v_mul_f32_e32 v9, v9, v4
	v_mul_f32_e32 v5, v5, v4
	v_mul_f32_e32 v0, v0, v4
	ds_write2_b32 v107, v8, v9 offset1:16
	ds_write2_b32 v107, v5, v0 offset0:32 offset1:48
	ds_read_b32 v4, v108
	ds_read_b32 v5, v109
	ds_read_b32 v8, v110
	ds_read2st64_b32 v[0:1], v111 offset1:1
	s_waitcnt lgkmcnt(3)
	v_fma_f32 v2, v18, v4, v2
	s_waitcnt lgkmcnt(0)
	v_add_f32_e32 v0, v1, v0
	v_fmac_f32_e32 v0, v4, v8
	v_max_f32_e32 v1, v5, v5
	v_max_f32_e64 v0, |v0|, v1
	v_div_scale_f32 v1, s[2:3], v0, v0, 1.0
	v_rcp_f32_e32 v5, v1
	s_nop 0
	v_fma_f32 v8, -v1, v5, 1.0
	v_fmac_f32_e32 v5, v8, v5
	v_div_scale_f32 v8, vcc, 1.0, v0, 1.0
	v_mul_f32_e32 v9, v8, v5
	v_fma_f32 v12, -v1, v9, v8
	v_fmac_f32_e32 v9, v12, v5
	v_fma_f32 v1, -v1, v9, v8
	v_div_fmas_f32 v1, v1, v5, v9
	v_div_fixup_f32 v0, v1, v0, 1.0
	v_fma_f32 v1, v30, v4, v14
	v_fma_f32 v5, v26, v4, v10
	v_mul_f32_e32 v1, v1, v0
	v_mul_f32_e32 v5, v5, v0
	ds_write2_b32 v112, v1, v5 offset1:16
	v_fma_f32 v1, v22, v4, v6
	v_mul_f32_e32 v1, v1, v0
	v_mul_f32_e32 v0, v2, v0
	ds_write2_b32 v112, v1, v0 offset0:32 offset1:48
	ds_read_b32 v2, v113
	ds_read_b32 v4, v114
	ds_read_b32 v5, v115
	ds_read2st64_b32 v[0:1], v116 offset1:1
	s_waitcnt lgkmcnt(3)
	v_fmac_f32_e32 v15, v31, v2
	v_fmac_f32_e32 v11, v27, v2
	v_fmac_f32_e32 v7, v23, v2
	s_waitcnt lgkmcnt(0)
	v_add_f32_e32 v0, v1, v0
	v_fmac_f32_e32 v0, v2, v5
	v_max_f32_e32 v1, v4, v4
	v_max_f32_e64 v0, |v0|, v1
	v_div_scale_f32 v1, s[2:3], v0, v0, 1.0
	v_rcp_f32_e32 v4, v1
	s_add_i32 s2, s16, s15
	v_fmac_f32_e32 v3, v19, v2
	s_add_i32 s2, s10, s2
	v_fma_f32 v5, -v1, v4, 1.0
	v_fmac_f32_e32 v4, v5, v4
	v_div_scale_f32 v5, vcc, 1.0, v0, 1.0
	v_mul_f32_e32 v6, v5, v4
	v_fma_f32 v8, -v1, v6, v5
	v_fmac_f32_e32 v6, v8, v4
	v_fma_f32 v1, -v1, v6, v5
	v_div_fmas_f32 v1, v1, v4, v6
	v_div_fixup_f32 v0, v1, v0, 1.0
	v_mul_f32_e32 v1, v15, v0
	v_mul_f32_e32 v4, v11, v0
	ds_write2_b32 v117, v1, v4 offset1:16
	v_mul_f32_e32 v1, v7, v0
	v_mul_f32_e32 v0, v3, v0
	s_add_i32 s78, s2, 0x84
	ds_write2_b32 v117, v1, v0 offset0:32 offset1:48
	s_waitcnt lgkmcnt(0)
	s_barrier
	s_and_saveexec_b64 s[2:3], s[40:41]
	s_xor_b64 s[2:3], exec, s[2:3]
	s_ashr_i32 s79, s78, 31
	s_or_saveexec_b64 s[94:95], s[2:3]
	s_sub_i32 s2, s17, s16
	s_sub_i32 s2, s2, s14
	s_add_i32 s2, s4, s2
	s_lshl_b32 s14, s2, 6
	v_mov_b64_e32 v[0:1], s[78:79]
	s_xor_b64 exec, exec, s[94:95]
	s_cbranch_execz .LBB0_521
;   __host__ __device__ __forceinline__ float* G() const { return (float*)(wsl() + OFF_G); }
;   __host__ __device__ __forceinline__ float* mst() const { return (float*)(wsl() + OFF_MST); }
; __device__ __forceinline__ float logsigmoidf_(float x) { return fminf(x, 0.0f) - log1pf(__expf(-fabsf(x))); }
; __device__ __forceinline__ void m3_phase(const Params& p, char* smem) {
;     ...
;       if (w == 0) {
;         int row = rowbase + mchunk_tok(dir, j, lane);
;         float gi = p.G()[(size_t)row * 16 + (2 * dir) * 4 + h] + p.mlstm_gate_b[(2 * dir) * 4 + h];
;         float gf = p.G()[(size_t)row * 16 + (2 * dir + 1) * 4 + h] + p.mlstm_gate_b[(2 * dir + 1) * 4 + h];
;         float bsum = logsigmoidf_(gf);
; #pragma unroll
;         for (int o = 1; o < 64; o <<= 1) { float t = __shfl_up(bsum, o); if (lane >= o) bsum += t; }
;         float cv = gi - bsum;
;         float pm = cv;
; #pragma unroll
;         for (int o = 1; o < 64; o <<= 1) { float t = __shfl_up(pm, o); if (lane >= o) pm = fmaxf(pm, t); }
;         float mprev = p.mst()[sidx];
;         float mt = fmaxf(bsum + mprev, bsum + pm);
;         cs[lane] = cv;
;         rt[lane] = bsum - mt;
;         wint[lane] = __expf(bsum + mprev - mt);
;         emt[lane] = __expf(-mt);
;       }
	v_add_u32_e32 v0, s14, v32
	v_xad_u32 v0, v0, 63, s12
	s_load_dwordx2 s[2:3], s[0:1], 0x90
	v_ashrrev_i32_e32 v1, 31, v0
	v_lshlrev_b64 v[0:1], 6, v[0:1]
	v_lshl_add_u64 v[0:1], s[92:93], 0, v[0:1]
	s_lshl_b32 s30, s13, 2
	v_lshl_add_u64 v[0:1], v[0:1], 0, s[30:31]
	v_mov_b32_e32 v3, s30
	global_load_dword v2, v[0:1], off offset:32
	s_waitcnt lgkmcnt(0)
	global_load_dword v4, v3, s[2:3] offset:32
	s_nop 0
	global_load_dword v0, v[0:1], off offset:48
	s_nop 0
	global_load_dword v1, v3, s[2:3] offset:48
	s_mov_b32 s2, 0xbfb8aa3b
	s_ashr_i32 s79, s78, 31
	s_waitcnt vmcnt(0)
	v_add_f32_e32 v0, v0, v1
	v_min_f32_e32 v3, 0, v0
	v_mul_f32_e64 v0, |v0|, s2
	v_exp_f32_e32 v5, v0
	s_mov_b32 s2, 0x3f2aaaab
	v_add_f32_e32 v6, 1.0, v5
	v_add_f32_e32 v0, -1.0, v6
	v_sub_f32_e32 v1, v0, v6
	v_add_f32_e32 v1, 1.0, v1
	v_sub_f32_e32 v0, v5, v0
	v_add_f32_e32 v7, v0, v1
	v_frexp_mant_f32_e32 v0, v6
	v_cmp_gt_f32_e32 vcc, s2, v0
	v_cvt_f64_f32_e32 v[0:1], v6
	v_frexp_exp_i32_f64_e32 v0, v[0:1]
	v_subbrev_co_u32_e32 v0, vcc, 0, v0, vcc
	v_sub_u32_e32 v1, 0, v0
	v_ldexp_f32 v6, v6, v1
	v_ldexp_f32 v1, v7, v1
	v_add_f32_e32 v7, -1.0, v6
	v_add_f32_e32 v8, 1.0, v7
	v_sub_f32_e32 v8, v6, v8
	v_add_f32_e32 v8, v1, v8
	v_add_f32_e32 v9, v7, v8
	v_sub_f32_e32 v7, v9, v7
	v_sub_f32_e32 v7, v8, v7
	v_add_f32_e32 v8, 1.0, v6
	v_add_f32_e32 v10, -1.0, v8
	v_sub_f32_e32 v6, v6, v10
	v_add_f32_e32 v1, v1, v6
	v_add_f32_e32 v6, v8, v1
	v_sub_f32_e32 v8, v6, v8
	v_sub_f32_e32 v1, v1, v8
	v_rcp_f32_e32 v8, v6
	v_cvt_f32_i32_e32 v0, v0
	s_mov_b32 s2, 0x3f317218
	v_mul_f32_e32 v10, v9, v8
	v_mul_f32_e32 v11, v6, v10
	v_fma_f32 v12, v10, v6, -v11
	v_fmac_f32_e32 v12, v10, v1
	v_add_f32_e32 v13, v11, v12
	v_sub_f32_e32 v14, v9, v13
	v_sub_f32_e32 v9, v9, v14
	v_sub_f32_e32 v11, v13, v11
	v_sub_f32_e32 v9, v9, v13
	v_add_f32_e32 v7, v7, v9
	v_sub_f32_e32 v9, v11, v12
	v_add_f32_e32 v7, v9, v7
	v_add_f32_e32 v9, v14, v7
	v_mul_f32_e32 v11, v8, v9
	v_mul_f32_e32 v12, v6, v11
	v_fma_f32 v6, v11, v6, -v12
	v_fmac_f32_e32 v6, v11, v1
	v_sub_f32_e32 v1, v14, v9
	v_add_f32_e32 v1, v7, v1
	v_add_f32_e32 v7, v12, v6
	v_sub_f32_e32 v13, v9, v7
	v_sub_f32_e32 v9, v9, v13
	v_sub_f32_e32 v12, v7, v12
	v_sub_f32_e32 v7, v9, v7
	v_add_f32_e32 v1, v1, v7
	v_sub_f32_e32 v6, v12, v6
	v_add_f32_e32 v1, v6, v1
	v_add_f32_e32 v6, v10, v11
	v_add_f32_e32 v1, v13, v1
	v_sub_f32_e32 v7, v6, v10
	v_mul_f32_e32 v1, v8, v1
	v_sub_f32_e32 v7, v11, v7
	v_add_f32_e32 v1, v7, v1
	v_mul_f32_e32 v10, 0x3f317218, v0
	v_add_f32_e32 v7, v6, v1
	v_fma_f32 v11, v0, s2, -v10
	v_mul_f32_e32 v8, v7, v7
	v_fmac_f32_e32 v11, 0xb102e308, v0
	v_sub_f32_e32 v0, v7, v6
	v_fmamk_f32 v9, v8, 0x3e9b6dac, v165
	v_sub_f32_e32 v0, v1, v0
	v_add_f32_e32 v1, v10, v11
	v_fmaak_f32 v9, v8, v9, 0x3f2aaada
	v_sub_f32_e32 v6, v1, v10
	v_ldexp_f32 v10, v7, 1
	v_mul_f32_e32 v7, v7, v8
	v_mul_f32_e32 v7, v7, v9
	v_add_f32_e32 v8, v10, v7
	v_sub_f32_e32 v9, v8, v10
	v_ldexp_f32 v0, v0, 1
	v_sub_f32_e32 v7, v7, v9
	v_add_f32_e32 v0, v0, v7
	v_add_f32_e32 v7, v8, v0
	v_sub_f32_e32 v8, v7, v8
	v_sub_f32_e32 v0, v0, v8
	v_add_f32_e32 v8, v1, v7
	v_sub_f32_e32 v9, v8, v1
	v_sub_f32_e32 v10, v8, v9
	v_sub_f32_e32 v6, v11, v6
	v_sub_f32_e32 v1, v1, v10
	v_sub_f32_e32 v7, v7, v9
	v_add_f32_e32 v1, v7, v1
	v_add_f32_e32 v7, v6, v0
	v_sub_f32_e32 v9, v7, v6
	v_sub_f32_e32 v10, v7, v9
	v_sub_f32_e32 v6, v6, v10
	v_sub_f32_e32 v0, v0, v9
	v_add_f32_e32 v1, v7, v1
	v_add_f32_e32 v0, v0, v6
	v_add_f32_e32 v6, v8, v1
	v_sub_f32_e32 v7, v6, v8
	v_sub_f32_e32 v1, v1, v7
	v_add_f32_e32 v0, v0, v1
	s_mov_b32 s2, 0x7f800000
	v_add_f32_e32 v0, v6, v0
	v_cmp_neq_f32_e32 vcc, s2, v5
	s_mov_b32 s2, 0x33800000
	s_nop 0
	v_cndmask_b32_e32 v0, v225, v0, vcc
	v_cmp_ngt_f32_e32 vcc, -1.0, v5
	s_nop 1
	v_cndmask_b32_e32 v0, v226, v0, vcc
	v_cmp_neq_f32_e32 vcc, -1.0, v5
	s_nop 1
	v_cndmask_b32_e32 v0, v227, v0, vcc
	v_cmp_lt_f32_e64 vcc, |v5|, s2
	s_lshl_b64 s[2:3], s[78:79], 2
	s_add_u32 s2, s7, s2
	v_cndmask_b32_e32 v0, v0, v5, vcc
	v_sub_f32_e32 v0, v3, v0
	ds_bpermute_b32 v1, v70, v0
	s_addc_u32 s3, s8, s3
	s_waitcnt lgkmcnt(0)
	v_add_f32_e32 v1, v0, v1
	v_cndmask_b32_e64 v0, v1, v0, s[48:49]
	ds_bpermute_b32 v1, v71, v0
	s_waitcnt lgkmcnt(0)
	v_add_f32_e32 v1, v0, v1
	v_cndmask_b32_e64 v0, v1, v0, s[50:51]
	ds_bpermute_b32 v1, v72, v0
	s_waitcnt lgkmcnt(0)
	v_add_f32_e32 v1, v0, v1
	v_cndmask_b32_e64 v0, v1, v0, s[52:53]
	ds_bpermute_b32 v1, v73, v0
	s_waitcnt lgkmcnt(0)
	v_add_f32_e32 v1, v0, v1
	v_cndmask_b32_e64 v0, v1, v0, s[54:55]
	ds_bpermute_b32 v1, v74, v0
	s_waitcnt lgkmcnt(0)
	v_add_f32_e32 v1, v0, v1
	v_cndmask_b32_e64 v0, v1, v0, s[56:57]
	ds_bpermute_b32 v1, v75, v0
	s_waitcnt lgkmcnt(0)
	v_add_f32_e32 v1, v0, v1
	v_cndmask_b32_e64 v0, v1, v0, s[58:59]
	v_add_f32_e32 v1, v2, v4
	v_sub_f32_e32 v1, v1, v0
	ds_bpermute_b32 v2, v70, v1
	ds_write_b32 v60, v1
	s_waitcnt lgkmcnt(1)
	v_max_f32_e32 v2, v2, v2
	v_max_f32_e32 v2, v1, v2
	v_cndmask_b32_e64 v2, v2, v1, s[48:49]
	ds_bpermute_b32 v3, v71, v2
	s_waitcnt lgkmcnt(0)
	v_max_f32_e32 v3, v3, v3
	v_max_f32_e32 v3, v2, v3
	v_cndmask_b32_e64 v2, v3, v2, s[50:51]
	ds_bpermute_b32 v3, v72, v2
	s_waitcnt lgkmcnt(0)
	v_max_f32_e32 v3, v3, v3
	v_max_f32_e32 v3, v2, v3
	v_cndmask_b32_e64 v2, v3, v2, s[52:53]
	ds_bpermute_b32 v3, v73, v2
	s_waitcnt lgkmcnt(0)
	v_max_f32_e32 v3, v3, v3
	v_max_f32_e32 v3, v2, v3
	v_cndmask_b32_e64 v2, v3, v2, s[54:55]
	ds_bpermute_b32 v3, v74, v2
	s_waitcnt lgkmcnt(0)
	v_max_f32_e32 v3, v3, v3
	v_max_f32_e32 v3, v2, v3
	v_cndmask_b32_e64 v2, v3, v2, s[56:57]
	ds_bpermute_b32 v3, v75, v2
	v_max_f32_e32 v4, v2, v2
	s_waitcnt lgkmcnt(0)
	v_max_f32_e32 v3, v3, v3
	v_max_f32_e32 v3, v4, v3
	v_cndmask_b32_e64 v2, v3, v2, s[58:59]
	global_load_dword v3, v167, s[2:3]
	v_add_f32_e32 v2, v0, v2
	s_waitcnt vmcnt(0)
	v_add_f32_e32 v3, v3, v0
	v_max_f32_e32 v2, v3, v2
	v_sub_f32_e32 v0, v0, v2
	ds_write_b32 v61, v0
	v_sub_f32_e32 v0, v3, v2
	v_mul_f32_e32 v0, 0x3fb8aa3b, v0
	v_exp_f32_e32 v0, v0
	ds_write_b32 v62, v0
	v_mul_f32_e32 v0, 0xbfb8aa3b, v2
	v_exp_f32_e32 v0, v0
	ds_write_b32 v63, v0
	v_mov_b64_e32 v[0:1], s[78:79]

;   __host__ __device__ __forceinline__ bf16_t* ACT() const { return (bf16_t*)(wsl() + OFF_ACT); }
;   __host__ __device__ __forceinline__ bf16_t* R() const { return (bf16_t*)(wsl() + OFF_R); }
; #define MFMA16(a, b, c) __builtin_amdgcn_mfma_f32_16x16x32_bf16(a, b, c, 0, 0, 0)
; __device__ __forceinline__ void m3_phase(const Params& p, char* smem) {
;     ...
;       for (int i = 0; i < 2; ++i) {
;         int idx = tid + i * NTHR;
;         int r = idx & 63, fc = (idx >> 6) * 8;
;         int row = rowbase + mchunk_tok(dir, j, r);
;         const bf16_t* src = p.ACT() + (size_t)row * PW;
;         uint4 qv = *(const uint4*)(src + 672 + h * 128 + fc);
;         uint4 kv = *(const uint4*)(src + 1184 + h * 128 + fc);
;         uint4 vv = *(const uint4*)(src + 1696 + h * 128 + fc);
;         *(uint4*)(Qs + r * 136 + fc) = qv;
;         *(uint4*)(Ks + r * 136 + fc) = kv;
;         const bf16_t* ve = (const bf16_t*)&vv;
; #pragma unroll
;         for (int e = 0; e < 8; ++e) Vt[(fc + e) * 72 + r] = ve[e];
;       }
;       {
;         const bf16_t* cst = p.R() + (size_t)sidx * 16384;
; #pragma unroll
;         for (int i = 0; i < 4; ++i) {
;           int idx = tid + i * NTHR;
;           int v = idx >> 4, kc = (idx & 15) * 8;
;           *(uint4*)(Cs + v * 136 + kc) = *(const uint4*)(cst + v * 128 + kc);
;         }
;       }
;       __syncthreads();
;       {
;         const int mi = w & 3, nb2 = (w >> 2) * 2;
;         f32x4 s2[2] = {(f32x4){0.f, 0.f, 0.f, 0.f}, (f32x4){0.f, 0.f, 0.f, 0.f}};
; #pragma unroll
;         for (int ks = 0; ks < 4; ++ks) {
;           bf16x8 a = *(const bf16x8*)(Qs + (mi * 16 + fr) * 136 + ks * 32 + fq * 8);
; #pragma unroll
;           for (int q = 0; q < 2; ++q) {
;             bf16x8 bb = *(const bf16x8*)(Ks + ((nb2 + q) * 16 + fr) * 136 + ks * 32 + fq * 8);
;             s2[q] = MFMA16(a, bb, s2[q]);
;           }
;         }
.LBB0_523:
	s_or_b64 exec, exec, s[2:3]
	v_or_b32_e32 v2, s14, v34
	s_lshl_b32 s13, s13, 7
	v_xad_u32 v4, v2, 63, s12
	v_mov_b64_e32 v[2:3], s[90:91]
	v_mad_i64_i32 v[2:3], s[2:3], v4, s84, v[2:3]
	s_lshl_b32 s30, s13, 1
	v_lshl_add_u64 v[14:15], v[2:3], 0, s[30:31]
	v_lshl_add_u64 v[10:11], v[14:15], 0, v[200:201]
	global_load_dwordx4 v[2:5], v[10:11], off offset:1344
	global_load_dwordx4 v[6:9], v[10:11], off offset:2368
	s_nop 0
	global_load_dwordx4 v[10:13], v[10:11], off offset:3392
	v_lshlrev_b64 v[0:1], 15, v[0:1]
	s_waitcnt vmcnt(2)
	ds_write_b128 v178, v[2:5]
	s_waitcnt vmcnt(1)
	ds_write_b128 v178, v[6:9] offset:17408
	s_waitcnt vmcnt(0)
	ds_write_b128 v171, v[10:13] offset:34816
	v_lshl_add_u64 v[10:11], v[14:15], 0, v[202:203]
	global_load_dwordx4 v[2:5], v[10:11], off offset:1344
	global_load_dwordx4 v[6:9], v[10:11], off offset:2368
	s_nop 0
	global_load_dwordx4 v[10:13], v[10:11], off offset:3392
	s_waitcnt vmcnt(2)
	ds_write_b128 v178, v[2:5] offset:8704
	s_waitcnt vmcnt(1)
	ds_write_b128 v178, v[6:9] offset:26112
	s_waitcnt vmcnt(0)
	ds_write_b128 v171, v[10:13] offset:44032
	v_lshl_add_u64 v[4:5], v[48:49], 0, v[0:1]
	v_lshl_add_u64 v[0:1], v[40:41], 1, v[4:5]
	global_load_dwordx4 v[0:3], v[0:1], off
	s_waitcnt vmcnt(0)
	ds_write_b128 v78, v[0:3]
	v_lshl_add_u64 v[0:1], v[42:43], 1, v[4:5]
	global_load_dwordx4 v[0:3], v[0:1], off
	s_waitcnt vmcnt(0)
	ds_write_b128 v79, v[0:3]
	v_lshl_add_u64 v[0:1], v[44:45], 1, v[4:5]
	global_load_dwordx4 v[0:3], v[0:1], off
	s_waitcnt vmcnt(0)
	ds_write_b128 v80, v[0:3]
	v_lshl_add_u64 v[0:1], v[46:47], 1, v[4:5]
	global_load_dwordx4 v[0:3], v[0:1], off
	s_waitcnt vmcnt(0)
	ds_write_b128 v81, v[0:3]
	s_waitcnt lgkmcnt(0)
	s_barrier
	ds_read_b128 v[160:163], v52
	ds_read_b128 v[172:175], v140 offset:17408
	ds_read_b128 v[204:207], v140 offset:21760
	ds_read_b128 v[208:211], v52 offset:64
	ds_read_b128 v[212:215], v140 offset:17472
	ds_read_b128 v[236:239], v140 offset:21824
	ds_read_b128 v[240:243], v52 offset:128
	ds_read_b128 v[244:247], v140 offset:17536
	s_waitcnt lgkmcnt(6)
	v_mfma_f32_16x16x32_bf16 v[4:7], v[160:163], v[172:175], 0
	ds_read_b128 v[248:251], v140 offset:21888
	s_waitcnt lgkmcnt(6)
	v_mfma_f32_16x16x32_bf16 v[0:3], v[160:163], v[204:207], 0
	ds_read_b128 v[172:175], v52 offset:192
	ds_read_b128 v[160:163], v140 offset:17600
	s_waitcnt lgkmcnt(6)
	v_mfma_f32_16x16x32_bf16 v[4:7], v[208:211], v[212:215], v[4:7]
	ds_read_b128 v[204:207], v140 offset:21952
	s_waitcnt lgkmcnt(6)
	v_mfma_f32_16x16x32_bf16 v[0:3], v[208:211], v[236:239], v[0:3]
	s_waitcnt lgkmcnt(4)
	v_mfma_f32_16x16x32_bf16 v[4:7], v[240:243], v[244:247], v[4:7]
	s_waitcnt lgkmcnt(3)
	v_mfma_f32_16x16x32_bf16 v[0:3], v[240:243], v[248:251], v[0:3]
	s_waitcnt lgkmcnt(1)
	v_mfma_f32_16x16x32_bf16 v[4:7], v[172:175], v[160:163], v[4:7]
	s_waitcnt lgkmcnt(0)
	v_mfma_f32_16x16x32_bf16 v[0:3], v[172:175], v[204:207], v[0:3]
	ds_read_b32 v10, v82
	v_mov_b32_e32 v11, 0
	v_mov_b32_e32 v8, 0
	s_and_saveexec_b64 s[2:3], s[60:61]
	s_cbranch_execz .LBB0_525
	ds_read_b32 v8, v84
	s_waitcnt lgkmcnt(0)
	v_add_f32_e32 v8, v10, v8
	v_mul_f32_e32 v8, 0x3fb8aa3b, v8
	v_exp_f32_e32 v8, v8
